# GEMM mainloops: removed the redundant s_setprio 0/1 pair between the two MFMA groups of each phase
# baseline (speedup 1.0000x reference)
; #define PG8_STAGE(bufoff, gbase, voff) do { _Pragma("unroll") for (int _i = 0; _i < 2; ++_i) \
;         __builtin_amdgcn_global_load_lds((const unsigned*)((const char*)(gbase) + (voff)[_i]), (LAS unsigned*)(lds + (bufoff) + ldsw + _i * 8192), 16, 0, 0); } while (0)
; #define PG8_LDA(dst, b, h) do { _Pragma("unroll") for (int m = 0; m < 4; ++m) _Pragma("unroll") for (int k = 0; k < 2; ++k) dst[m][k] = *(const LAS bf16x8*)(lds + PG8_SA(b, h) + aoff + m * 2048 + k * 1024); } while (0)
; #define PG8_LDB(dst, b, h) do { _Pragma("unroll") for (int n = 0; n < 2; ++n) _Pragma("unroll") for (int k = 0; k < 2; ++k) dst[n][k] = *(const LAS bf16x8*)(lds + PG8_SB(b, h) + boff + n * 2048 + k * 1024); } while (0)
; #define PG8_WAIT_V(n) asm volatile("s_waitcnt vmcnt(" #n ")" ::: "memory")
; #define PG8_BAR __builtin_amdgcn_s_barrier()
; template <class Epi, class Sched>
; __device__ __forceinline__ void gemm_phase(LAS unsigned char* lds, const Gemm g, const Sched S, const Epi E, const int tid) {
;     ...
;         for (int t = 0; t < nt; t += 2) {
;             const bool last = (t == nt - 2);
;             const char* a1 = cA + (size_t)(t + 1) * kstep;
;             const char* a2 = last ? nA : cA + (size_t)(t + 2) * kstep; const char* b2 = last ? nB : cB + (size_t)(t + 2) * kstep;
;             const char* a3 = a2 + kstep; const char* b3 = b2 + kstep;
;             PG8_LDB(B0, 0, 0); PG8_LDB(B1, 0, 1); PG8_SCHED; PG8_LDA(At, 0, 0); PG8_STAGE(PG8_SA(1, 1), a1 + hstepA, voffA);
;             PG8_WAIT_V(8); PG8_WAIT_L(0); PG8_BAR; PG8_MMA(0, 0, At, B0); PG8_MMA(0, 1, At, B1); PG8_BAR; PG8_SCHED;
;             PG8_LDA(At, 0, 1); PG8_STAGE(PG8_SB(0, 0), b2, voffB); PG8_STAGE(PG8_SB(0, 1), b2 + hstepB, voffB); PG8_STAGE(PG8_SA(0, 0), a2, voffA);
;             PG8_WAIT_V(8); PG8_WAIT_L(0); PG8_BAR; PG8_MMA(1, 0, At, B0); PG8_MMA(1, 1, At, B1); PG8_BAR; PG8_SCHED;
;             PG8_LDB(B0, 1, 0); PG8_LDB(B1, 1, 1); PG8_SCHED; PG8_LDA(At, 1, 0); PG8_STAGE(PG8_SA(0, 1), a2 + hstepA, voffA);
;             PG8_WAIT_V(8); PG8_WAIT_L(0); PG8_BAR; PG8_MMA(0, 0, At, B0); PG8_MMA(0, 1, At, B1); PG8_BAR; PG8_SCHED;
;             PG8_LDA(At, 1, 1); PG8_STAGE(PG8_SB(1, 0), b3, voffB); PG8_STAGE(PG8_SB(1, 1), b3 + hstepB, voffB); PG8_STAGE(PG8_SA(1, 0), a3, voffA);
;             PG8_WAIT_V(8); PG8_WAIT_L(0); PG8_BAR; PG8_MMA(1, 0, At, B0); PG8_MMA(1, 1, At, B1); PG8_BAR; PG8_SCHED;
;         }
.LBB0_299:
	s_add_u32 s10, s22, 0xfffc0080
	s_addc_u32 s11, s23, -1
	s_add_i32 s44, 0, 0x10000
	s_cmp_eq_u32 vcc_hi, 28
	s_cselect_b32 s29, s93, s11
	s_cselect_b32 s28, s94, s10
	v_add_u32_e32 v154, s44, v167
	s_cselect_b32 s27, s95, vcc_lo
	s_cselect_b32 s26, s96, s97
	s_add_i32 s45, 0, 0x14000
	ds_read_b128 v[98:101], v154
	ds_read_b128 v[102:105], v154 offset:1024
	ds_read_b128 v[150:153], v154 offset:2048
	ds_read_b128 v[180:183], v154 offset:3072
	v_add_u32_e32 v154, s45, v167
	ds_read_b128 v[184:187], v154
	ds_read_b128 v[188:191], v154 offset:1024
	ds_read_b128 v[192:195], v154 offset:2048
	ds_read_b128 v[196:199], v154 offset:3072
	v_lshl_add_u64 v[154:155], s[22:23], 0, v[148:149]
	s_add_i32 m0, s47, 0xc000
	ds_read_b128 v[200:203], v179
	ds_read_b128 v[204:207], v179 offset:1024
	ds_read_b128 v[208:211], v179 offset:2048
	ds_read_b128 v[212:215], v179 offset:3072
	ds_read_b128 v[216:219], v179 offset:4096
	ds_read_b128 v[220:223], v179 offset:5120
	ds_read_b128 v[224:227], v179 offset:6144
	ds_read_b128 v[228:231], v179 offset:7168
	global_load_lds_dwordx4 v[154:155], off
	v_lshl_add_u64 v[154:155], s[22:23], 0, v[146:147]
	s_add_i32 m0, s47, 0xe000
	s_nop 0
	global_load_lds_dwordx4 v[154:155], off
	s_waitcnt vmcnt(8)
	s_waitcnt lgkmcnt(0)
	s_barrier
	s_setprio 1
	s_waitcnt lgkmcnt(0)
	v_mfma_f32_16x16x32_bf16 v[134:137], v[98:101], v[200:203], v[134:137]
	v_mfma_f32_16x16x32_bf16 v[130:133], v[150:153], v[200:203], v[130:133]
	v_mfma_f32_16x16x32_bf16 v[126:129], v[98:101], v[208:211], v[126:129]
	v_mfma_f32_16x16x32_bf16 v[122:125], v[150:153], v[208:211], v[122:125]
	v_mfma_f32_16x16x32_bf16 v[118:121], v[98:101], v[216:219], v[118:121]
	v_mfma_f32_16x16x32_bf16 v[114:117], v[150:153], v[216:219], v[114:117]
	v_mfma_f32_16x16x32_bf16 v[110:113], v[98:101], v[224:227], v[110:113]
	v_mfma_f32_16x16x32_bf16 v[106:109], v[150:153], v[224:227], v[106:109]
	v_mfma_f32_16x16x32_bf16 v[134:137], v[102:105], v[204:207], v[134:137]
	v_mfma_f32_16x16x32_bf16 v[130:133], v[180:183], v[204:207], v[130:133]
	v_mfma_f32_16x16x32_bf16 v[126:129], v[102:105], v[212:215], v[126:129]
	v_mfma_f32_16x16x32_bf16 v[122:125], v[180:183], v[212:215], v[122:125]
	v_mfma_f32_16x16x32_bf16 v[118:121], v[102:105], v[220:223], v[118:121]
	v_mfma_f32_16x16x32_bf16 v[114:117], v[180:183], v[220:223], v[114:117]
	v_mfma_f32_16x16x32_bf16 v[110:113], v[102:105], v[228:231], v[110:113]
	v_mfma_f32_16x16x32_bf16 v[106:109], v[180:183], v[228:231], v[106:109]
	v_mfma_f32_16x16x32_bf16 v[62:65], v[184:187], v[200:203], v[62:65]
	v_mfma_f32_16x16x32_bf16 v[58:61], v[192:195], v[200:203], v[58:61]
	v_mfma_f32_16x16x32_bf16 v[54:57], v[184:187], v[208:211], v[54:57]
	v_mfma_f32_16x16x32_bf16 v[50:53], v[192:195], v[208:211], v[50:53]
	v_mfma_f32_16x16x32_bf16 v[46:49], v[184:187], v[216:219], v[46:49]
	v_mfma_f32_16x16x32_bf16 v[42:45], v[192:195], v[216:219], v[42:45]
	v_mfma_f32_16x16x32_bf16 v[38:41], v[184:187], v[224:227], v[38:41]
	v_mfma_f32_16x16x32_bf16 v[34:37], v[192:195], v[224:227], v[34:37]
	v_mfma_f32_16x16x32_bf16 v[62:65], v[188:191], v[204:207], v[62:65]
	v_mfma_f32_16x16x32_bf16 v[58:61], v[196:199], v[204:207], v[58:61]
	v_mfma_f32_16x16x32_bf16 v[54:57], v[188:191], v[212:215], v[54:57]
	v_mfma_f32_16x16x32_bf16 v[50:53], v[196:199], v[212:215], v[50:53]
	v_mfma_f32_16x16x32_bf16 v[46:49], v[188:191], v[220:223], v[46:49]
	v_mfma_f32_16x16x32_bf16 v[42:45], v[196:199], v[220:223], v[42:45]
	v_mfma_f32_16x16x32_bf16 v[38:41], v[188:191], v[228:231], v[38:41]
	v_mfma_f32_16x16x32_bf16 v[34:37], v[196:199], v[228:231], v[34:37]
	s_setprio 0
	s_barrier
	s_add_i32 s10, s44, s46
	v_lshl_add_u64 v[154:155], s[26:27], 0, v[142:143]
	s_mov_b32 m0, s10
	ds_read_b128 v[200:203], v179 offset:16384
	ds_read_b128 v[204:207], v179 offset:17408
	ds_read_b128 v[208:211], v179 offset:18432
	ds_read_b128 v[212:215], v179 offset:19456
	ds_read_b128 v[216:219], v179 offset:20480
	ds_read_b128 v[220:223], v179 offset:21504
	ds_read_b128 v[224:227], v179 offset:22528
	ds_read_b128 v[228:231], v179 offset:23552
	global_load_lds_dwordx4 v[154:155], off
	s_add_i32 m0, s10, 0x2000
	s_add_u32 s10, s26, 0x80000
	v_lshl_add_u64 v[232:233], s[26:27], 0, v[138:139]
	s_addc_u32 s11, s27, 0
	s_add_i32 s45, s45, s46
	global_load_lds_dwordx4 v[232:233], off
	v_lshl_add_u64 v[234:235], s[10:11], 0, v[142:143]
	s_mov_b32 m0, s45
	v_lshl_add_u64 v[246:247], s[28:29], 0, v[140:141]
	global_load_lds_dwordx4 v[234:235], off
	v_lshl_add_u64 v[234:235], s[10:11], 0, v[138:139]
	s_add_i32 m0, s45, 0x2000
	s_nop 0
	global_load_lds_dwordx4 v[234:235], off
	v_lshl_add_u64 v[234:235], s[28:29], 0, v[144:145]
	s_mov_b32 m0, s47
	s_nop 0
	global_load_lds_dwordx4 v[234:235], off
	s_mov_b32 m0, s48
	s_nop 0
	global_load_lds_dwordx4 v[246:247], off
	s_waitcnt vmcnt(8)
	s_waitcnt lgkmcnt(0)
	s_barrier
; #define PG8_STAGE(bufoff, gbase, voff) do { _Pragma("unroll") for (int _i = 0; _i < 2; ++_i) \
;         __builtin_amdgcn_global_load_lds((const unsigned*)((const char*)(gbase) + (voff)[_i]), (LAS unsigned*)(lds + (bufoff) + ldsw + _i * 8192), 16, 0, 0); } while (0)
; #define PG8_LDA(dst, b, h) do { _Pragma("unroll") for (int m = 0; m < 4; ++m) _Pragma("unroll") for (int k = 0; k < 2; ++k) dst[m][k] = *(const LAS bf16x8*)(lds + PG8_SA(b, h) + aoff + m * 2048 + k * 1024); } while (0)
; #define PG8_LDB(dst, b, h) do { _Pragma("unroll") for (int n = 0; n < 2; ++n) _Pragma("unroll") for (int k = 0; k < 2; ++k) dst[n][k] = *(const LAS bf16x8*)(lds + PG8_SB(b, h) + boff + n * 2048 + k * 1024); } while (0)
; #define PG8_WAIT_V(n) asm volatile("s_waitcnt vmcnt(" #n ")" ::: "memory")
; #define PG8_BAR __builtin_amdgcn_s_barrier()
; template <class Epi, class Sched>
; __device__ __forceinline__ void gemm_phase(LAS unsigned char* lds, const Gemm g, const Sched S, const Epi E, const int tid) {
;     ...
;         for (int t = 0; t < nt; t += 2) {
;             const bool last = (t == nt - 2);
;             const char* a1 = cA + (size_t)(t + 1) * kstep;
;             const char* a2 = last ? nA : cA + (size_t)(t + 2) * kstep; const char* b2 = last ? nB : cB + (size_t)(t + 2) * kstep;
;             const char* a3 = a2 + kstep; const char* b3 = b2 + kstep;
;             PG8_LDB(B0, 0, 0); PG8_LDB(B1, 0, 1); PG8_SCHED; PG8_LDA(At, 0, 0); PG8_STAGE(PG8_SA(1, 1), a1 + hstepA, voffA);
;             PG8_WAIT_V(8); PG8_WAIT_L(0); PG8_BAR; PG8_MMA(0, 0, At, B0); PG8_MMA(0, 1, At, B1); PG8_BAR; PG8_SCHED;
;             PG8_LDA(At, 0, 1); PG8_STAGE(PG8_SB(0, 0), b2, voffB); PG8_STAGE(PG8_SB(0, 1), b2 + hstepB, voffB); PG8_STAGE(PG8_SA(0, 0), a2, voffA);
;             PG8_WAIT_V(8); PG8_WAIT_L(0); PG8_BAR; PG8_MMA(1, 0, At, B0); PG8_MMA(1, 1, At, B1); PG8_BAR; PG8_SCHED;
;             PG8_LDB(B0, 1, 0); PG8_LDB(B1, 1, 1); PG8_SCHED; PG8_LDA(At, 1, 0); PG8_STAGE(PG8_SA(0, 1), a2 + hstepA, voffA);
;             PG8_WAIT_V(8); PG8_WAIT_L(0); PG8_BAR; PG8_MMA(0, 0, At, B0); PG8_MMA(0, 1, At, B1); PG8_BAR; PG8_SCHED;
;             PG8_LDA(At, 1, 1); PG8_STAGE(PG8_SB(1, 0), b3, voffB); PG8_STAGE(PG8_SB(1, 1), b3 + hstepB, voffB); PG8_STAGE(PG8_SA(1, 0), a3, voffA);
;             PG8_WAIT_V(8); PG8_WAIT_L(0); PG8_BAR; PG8_MMA(1, 0, At, B0); PG8_MMA(1, 1, At, B1); PG8_BAR; PG8_SCHED;
;         }
	s_setprio 1
	s_waitcnt lgkmcnt(0)
	v_mfma_f32_16x16x32_bf16 v[94:97], v[98:101], v[200:203], v[94:97]
	v_mfma_f32_16x16x32_bf16 v[90:93], v[150:153], v[200:203], v[90:93]
	v_mfma_f32_16x16x32_bf16 v[86:89], v[98:101], v[208:211], v[86:89]
	v_mfma_f32_16x16x32_bf16 v[82:85], v[150:153], v[208:211], v[82:85]
	v_mfma_f32_16x16x32_bf16 v[78:81], v[98:101], v[216:219], v[78:81]
	v_mfma_f32_16x16x32_bf16 v[74:77], v[150:153], v[216:219], v[74:77]
	v_mfma_f32_16x16x32_bf16 v[70:73], v[98:101], v[224:227], v[70:73]
	v_mfma_f32_16x16x32_bf16 v[66:69], v[150:153], v[224:227], v[66:69]
	v_mfma_f32_16x16x32_bf16 v[94:97], v[102:105], v[204:207], v[94:97]
	v_mfma_f32_16x16x32_bf16 v[90:93], v[180:183], v[204:207], v[90:93]
	v_mfma_f32_16x16x32_bf16 v[86:89], v[102:105], v[212:215], v[86:89]
	v_mfma_f32_16x16x32_bf16 v[82:85], v[180:183], v[212:215], v[82:85]
	v_mfma_f32_16x16x32_bf16 v[78:81], v[102:105], v[220:223], v[78:81]
	v_mfma_f32_16x16x32_bf16 v[74:77], v[180:183], v[220:223], v[74:77]
	v_mfma_f32_16x16x32_bf16 v[70:73], v[102:105], v[228:231], v[70:73]
	v_mfma_f32_16x16x32_bf16 v[66:69], v[180:183], v[228:231], v[66:69]
	v_mfma_f32_16x16x32_bf16 v[30:33], v[184:187], v[200:203], v[30:33]
	v_mfma_f32_16x16x32_bf16 v[26:29], v[192:195], v[200:203], v[26:29]
	v_mfma_f32_16x16x32_bf16 v[22:25], v[184:187], v[208:211], v[22:25]
	v_mfma_f32_16x16x32_bf16 v[18:21], v[192:195], v[208:211], v[18:21]
	v_mfma_f32_16x16x32_bf16 v[14:17], v[184:187], v[216:219], v[14:17]
	v_mfma_f32_16x16x32_bf16 v[10:13], v[192:195], v[216:219], v[10:13]
	v_mfma_f32_16x16x32_bf16 v[6:9], v[184:187], v[224:227], v[6:9]
	v_mfma_f32_16x16x32_bf16 v[2:5], v[192:195], v[224:227], v[2:5]
	v_mfma_f32_16x16x32_bf16 v[30:33], v[188:191], v[204:207], v[30:33]
	v_mfma_f32_16x16x32_bf16 v[26:29], v[196:199], v[204:207], v[26:29]
	v_mfma_f32_16x16x32_bf16 v[22:25], v[188:191], v[212:215], v[22:25]
	v_mfma_f32_16x16x32_bf16 v[18:21], v[196:199], v[212:215], v[18:21]
	v_mfma_f32_16x16x32_bf16 v[14:17], v[188:191], v[220:223], v[14:17]
	v_mfma_f32_16x16x32_bf16 v[10:13], v[196:199], v[220:223], v[10:13]
	v_mfma_f32_16x16x32_bf16 v[6:9], v[188:191], v[228:231], v[6:9]
	v_mfma_f32_16x16x32_bf16 v[2:5], v[196:199], v[228:231], v[2:5]
	s_setprio 0
	s_barrier
	s_add_i32 s45, 0, 0x18000
	s_add_i32 s6, 0, 0x1c000
	v_add_u32_e32 v180, s45, v167
	v_add_u32_e32 v196, s6, v167
	ds_read_b128 v[98:101], v180
	ds_read_b128 v[102:105], v180 offset:1024
	ds_read_b128 v[150:153], v180 offset:2048
	ds_read_b128 v[180:183], v180 offset:3072
	ds_read_b128 v[184:187], v196
	ds_read_b128 v[188:191], v196 offset:1024
	ds_read_b128 v[192:195], v196 offset:2048
	ds_read_b128 v[196:199], v196 offset:3072
	s_add_u32 s10, s28, 0x40000
	s_addc_u32 s11, s29, 0
	s_mov_b32 m0, s49
	v_lshl_add_u64 v[248:249], s[10:11], 0, v[144:145]
	ds_read_b128 v[200:203], v179 offset:32768
	ds_read_b128 v[204:207], v179 offset:33792
	ds_read_b128 v[208:211], v179 offset:34816
	ds_read_b128 v[212:215], v179 offset:35840
	ds_read_b128 v[216:219], v179 offset:36864
	ds_read_b128 v[220:223], v179 offset:37888
	ds_read_b128 v[224:227], v179 offset:38912
	ds_read_b128 v[228:231], v179 offset:39936
	global_load_lds_dwordx4 v[248:249], off
	v_lshl_add_u64 v[248:249], s[10:11], 0, v[140:141]
	s_mov_b32 m0, s62
	s_nop 0
	global_load_lds_dwordx4 v[248:249], off
	s_waitcnt vmcnt(8)
	s_waitcnt lgkmcnt(0)
	s_barrier
	s_setprio 1
	s_waitcnt lgkmcnt(0)
	v_mfma_f32_16x16x32_bf16 v[134:137], v[98:101], v[200:203], v[134:137]
	v_mfma_f32_16x16x32_bf16 v[130:133], v[150:153], v[200:203], v[130:133]
	v_mfma_f32_16x16x32_bf16 v[126:129], v[98:101], v[208:211], v[126:129]
	v_mfma_f32_16x16x32_bf16 v[122:125], v[150:153], v[208:211], v[122:125]
	v_mfma_f32_16x16x32_bf16 v[118:121], v[98:101], v[216:219], v[118:121]
	v_mfma_f32_16x16x32_bf16 v[114:117], v[150:153], v[216:219], v[114:117]
	v_mfma_f32_16x16x32_bf16 v[110:113], v[98:101], v[224:227], v[110:113]
	v_mfma_f32_16x16x32_bf16 v[106:109], v[150:153], v[224:227], v[106:109]
	v_mfma_f32_16x16x32_bf16 v[134:137], v[102:105], v[204:207], v[134:137]
	v_mfma_f32_16x16x32_bf16 v[130:133], v[180:183], v[204:207], v[130:133]
	v_mfma_f32_16x16x32_bf16 v[126:129], v[102:105], v[212:215], v[126:129]
	v_mfma_f32_16x16x32_bf16 v[122:125], v[180:183], v[212:215], v[122:125]
	v_mfma_f32_16x16x32_bf16 v[118:121], v[102:105], v[220:223], v[118:121]
	v_mfma_f32_16x16x32_bf16 v[114:117], v[180:183], v[220:223], v[114:117]
	v_mfma_f32_16x16x32_bf16 v[110:113], v[102:105], v[228:231], v[110:113]
	v_mfma_f32_16x16x32_bf16 v[106:109], v[180:183], v[228:231], v[106:109]
	v_mfma_f32_16x16x32_bf16 v[62:65], v[184:187], v[200:203], v[62:65]
	v_mfma_f32_16x16x32_bf16 v[58:61], v[192:195], v[200:203], v[58:61]
	v_mfma_f32_16x16x32_bf16 v[54:57], v[184:187], v[208:211], v[54:57]
	v_mfma_f32_16x16x32_bf16 v[50:53], v[192:195], v[208:211], v[50:53]
	v_mfma_f32_16x16x32_bf16 v[46:49], v[184:187], v[216:219], v[46:49]
	v_mfma_f32_16x16x32_bf16 v[42:45], v[192:195], v[216:219], v[42:45]
	v_mfma_f32_16x16x32_bf16 v[38:41], v[184:187], v[224:227], v[38:41]
	v_mfma_f32_16x16x32_bf16 v[34:37], v[192:195], v[224:227], v[34:37]
	v_mfma_f32_16x16x32_bf16 v[62:65], v[188:191], v[204:207], v[62:65]
	v_mfma_f32_16x16x32_bf16 v[58:61], v[196:199], v[204:207], v[58:61]
	v_mfma_f32_16x16x32_bf16 v[54:57], v[188:191], v[212:215], v[54:57]
	v_mfma_f32_16x16x32_bf16 v[50:53], v[196:199], v[212:215], v[50:53]
	v_mfma_f32_16x16x32_bf16 v[46:49], v[188:191], v[220:223], v[46:49]
	v_mfma_f32_16x16x32_bf16 v[42:45], v[196:199], v[220:223], v[42:45]
	v_mfma_f32_16x16x32_bf16 v[38:41], v[188:191], v[228:231], v[38:41]
	v_mfma_f32_16x16x32_bf16 v[34:37], v[196:199], v[228:231], v[34:37]
	s_setprio 0
	s_barrier
; #define PG8_STAGE(bufoff, gbase, voff) do { _Pragma("unroll") for (int _i = 0; _i < 2; ++_i) \
;         __builtin_amdgcn_global_load_lds((const unsigned*)((const char*)(gbase) + (voff)[_i]), (LAS unsigned*)(lds + (bufoff) + ldsw + _i * 8192), 16, 0, 0); } while (0)
; #define PG8_LDA(dst, b, h) do { _Pragma("unroll") for (int m = 0; m < 4; ++m) _Pragma("unroll") for (int k = 0; k < 2; ++k) dst[m][k] = *(const LAS bf16x8*)(lds + PG8_SA(b, h) + aoff + m * 2048 + k * 1024); } while (0)
; #define PG8_LDB(dst, b, h) do { _Pragma("unroll") for (int n = 0; n < 2; ++n) _Pragma("unroll") for (int k = 0; k < 2; ++k) dst[n][k] = *(const LAS bf16x8*)(lds + PG8_SB(b, h) + boff + n * 2048 + k * 1024); } while (0)
; #define PG8_WAIT_V(n) asm volatile("s_waitcnt vmcnt(" #n ")" ::: "memory")
; #define PG8_BAR __builtin_amdgcn_s_barrier()
; template <class Epi, class Sched>
; __device__ __forceinline__ void gemm_phase(LAS unsigned char* lds, const Gemm g, const Sched S, const Epi E, const int tid) {
;     ...
;         for (int t = 0; t < nt; t += 2) {
;             const bool last = (t == nt - 2);
;             const char* a1 = cA + (size_t)(t + 1) * kstep;
;             const char* a2 = last ? nA : cA + (size_t)(t + 2) * kstep; const char* b2 = last ? nB : cB + (size_t)(t + 2) * kstep;
;             const char* a3 = a2 + kstep; const char* b3 = b2 + kstep;
;             PG8_LDB(B0, 0, 0); PG8_LDB(B1, 0, 1); PG8_SCHED; PG8_LDA(At, 0, 0); PG8_STAGE(PG8_SA(1, 1), a1 + hstepA, voffA);
;             PG8_WAIT_V(8); PG8_WAIT_L(0); PG8_BAR; PG8_MMA(0, 0, At, B0); PG8_MMA(0, 1, At, B1); PG8_BAR; PG8_SCHED;
;             PG8_LDA(At, 0, 1); PG8_STAGE(PG8_SB(0, 0), b2, voffB); PG8_STAGE(PG8_SB(0, 1), b2 + hstepB, voffB); PG8_STAGE(PG8_SA(0, 0), a2, voffA);
;             PG8_WAIT_V(8); PG8_WAIT_L(0); PG8_BAR; PG8_MMA(1, 0, At, B0); PG8_MMA(1, 1, At, B1); PG8_BAR; PG8_SCHED;
;             PG8_LDB(B0, 1, 0); PG8_LDB(B1, 1, 1); PG8_SCHED; PG8_LDA(At, 1, 0); PG8_STAGE(PG8_SA(0, 1), a2 + hstepA, voffA);
;             PG8_WAIT_V(8); PG8_WAIT_L(0); PG8_BAR; PG8_MMA(0, 0, At, B0); PG8_MMA(0, 1, At, B1); PG8_BAR; PG8_SCHED;
;             PG8_LDA(At, 1, 1); PG8_STAGE(PG8_SB(1, 0), b3, voffB); PG8_STAGE(PG8_SB(1, 1), b3 + hstepB, voffB); PG8_STAGE(PG8_SA(1, 0), a3, voffA);
;             PG8_WAIT_V(8); PG8_WAIT_L(0); PG8_BAR; PG8_MMA(1, 0, At, B0); PG8_MMA(1, 1, At, B1); PG8_BAR; PG8_SCHED;
;         }
	s_add_i32 s7, s45, s46
	v_lshl_add_u64 v[154:155], v[154:155], 0, s[64:65]
	s_mov_b32 m0, s7
	ds_read_b128 v[200:203], v179 offset:49152
	ds_read_b128 v[204:207], v179 offset:50176
	ds_read_b128 v[208:211], v179 offset:51200
	ds_read_b128 v[212:215], v179 offset:52224
	ds_read_b128 v[216:219], v179 offset:53248
	ds_read_b128 v[220:223], v179 offset:54272
	ds_read_b128 v[224:227], v179 offset:55296
	ds_read_b128 v[228:231], v179 offset:56320
	global_load_lds_dwordx4 v[154:155], off
	s_add_i32 m0, s7, 0x2000
	s_add_u32 s10, s26, 0x80080
	v_lshl_add_u64 v[154:155], v[232:233], 0, s[64:65]
	s_addc_u32 s11, s27, 0
	s_add_i32 s6, s6, s46
	global_load_lds_dwordx4 v[154:155], off
	v_lshl_add_u64 v[154:155], s[10:11], 0, v[142:143]
	s_mov_b32 m0, s6
	s_nop 0
	global_load_lds_dwordx4 v[154:155], off
	v_lshl_add_u64 v[154:155], s[10:11], 0, v[138:139]
	s_add_i32 m0, s6, 0x2000
	s_nop 0
	global_load_lds_dwordx4 v[154:155], off
	v_lshl_add_u64 v[154:155], v[234:235], 0, s[64:65]
	s_mov_b32 m0, s84
	s_nop 0
	global_load_lds_dwordx4 v[154:155], off
	v_lshl_add_u64 v[154:155], v[246:247], 0, s[64:65]
	s_mov_b32 m0, s85
	s_nop 0
	global_load_lds_dwordx4 v[154:155], off
	s_waitcnt vmcnt(8)
	s_waitcnt lgkmcnt(0)
	s_barrier
	s_setprio 1
	s_waitcnt lgkmcnt(0)
	v_mfma_f32_16x16x32_bf16 v[94:97], v[98:101], v[200:203], v[94:97]
	v_mfma_f32_16x16x32_bf16 v[90:93], v[150:153], v[200:203], v[90:93]
	v_mfma_f32_16x16x32_bf16 v[86:89], v[98:101], v[208:211], v[86:89]
	v_mfma_f32_16x16x32_bf16 v[82:85], v[150:153], v[208:211], v[82:85]
	v_mfma_f32_16x16x32_bf16 v[78:81], v[98:101], v[216:219], v[78:81]
	v_mfma_f32_16x16x32_bf16 v[74:77], v[150:153], v[216:219], v[74:77]
	v_mfma_f32_16x16x32_bf16 v[70:73], v[98:101], v[224:227], v[70:73]
	v_mfma_f32_16x16x32_bf16 v[66:69], v[150:153], v[224:227], v[66:69]
	v_mfma_f32_16x16x32_bf16 v[94:97], v[102:105], v[204:207], v[94:97]
	v_mfma_f32_16x16x32_bf16 v[90:93], v[180:183], v[204:207], v[90:93]
	v_mfma_f32_16x16x32_bf16 v[86:89], v[102:105], v[212:215], v[86:89]
	v_mfma_f32_16x16x32_bf16 v[82:85], v[180:183], v[212:215], v[82:85]
	v_mfma_f32_16x16x32_bf16 v[78:81], v[102:105], v[220:223], v[78:81]
	v_mfma_f32_16x16x32_bf16 v[74:77], v[180:183], v[220:223], v[74:77]
	v_mfma_f32_16x16x32_bf16 v[70:73], v[102:105], v[228:231], v[70:73]
	v_mfma_f32_16x16x32_bf16 v[66:69], v[180:183], v[228:231], v[66:69]
	v_mfma_f32_16x16x32_bf16 v[30:33], v[184:187], v[200:203], v[30:33]
	v_mfma_f32_16x16x32_bf16 v[26:29], v[192:195], v[200:203], v[26:29]
	v_mfma_f32_16x16x32_bf16 v[22:25], v[184:187], v[208:211], v[22:25]
	v_mfma_f32_16x16x32_bf16 v[18:21], v[192:195], v[208:211], v[18:21]
	v_mfma_f32_16x16x32_bf16 v[14:17], v[184:187], v[216:219], v[14:17]
	v_mfma_f32_16x16x32_bf16 v[10:13], v[192:195], v[216:219], v[10:13]
	v_mfma_f32_16x16x32_bf16 v[6:9], v[184:187], v[224:227], v[6:9]
	v_mfma_f32_16x16x32_bf16 v[2:5], v[192:195], v[224:227], v[2:5]
	v_mfma_f32_16x16x32_bf16 v[30:33], v[188:191], v[204:207], v[30:33]
	v_mfma_f32_16x16x32_bf16 v[26:29], v[196:199], v[204:207], v[26:29]
	v_mfma_f32_16x16x32_bf16 v[22:25], v[188:191], v[212:215], v[22:25]
	v_mfma_f32_16x16x32_bf16 v[18:21], v[196:199], v[212:215], v[18:21]
	v_mfma_f32_16x16x32_bf16 v[14:17], v[188:191], v[220:223], v[14:17]
	v_mfma_f32_16x16x32_bf16 v[10:13], v[196:199], v[220:223], v[10:13]
	v_mfma_f32_16x16x32_bf16 v[6:9], v[188:191], v[228:231], v[6:9]
	v_mfma_f32_16x16x32_bf16 v[2:5], v[196:199], v[228:231], v[2:5]
	s_setprio 0
	s_barrier
	s_add_i32 vcc_hi, vcc_hi, 2
	s_add_u32 s97, s97, 0x100
	s_addc_u32 vcc_lo, vcc_lo, 0
	s_add_u32 s22, s22, 0x100
	s_addc_u32 s23, s23, 0
	s_cmp_gt_u32 vcc_hi, 29
	s_cbranch_scc0 .LBB0_299
	s_and_b64 vcc, exec, s[18:19]
	s_cbranch_vccz .LBB0_302
	s_barrier

; #define PG8_STAGE(bufoff, gbase, voff) do { _Pragma("unroll") for (int _i = 0; _i < 2; ++_i) \
;         __builtin_amdgcn_global_load_lds((const unsigned*)((const char*)(gbase) + (voff)[_i]), (LAS unsigned*)(lds + (bufoff) + ldsw + _i * 8192), 16, 0, 0); } while (0)
; #define PG8_LDA(dst, b, h) do { _Pragma("unroll") for (int m = 0; m < 4; ++m) _Pragma("unroll") for (int k = 0; k < 2; ++k) dst[m][k] = *(const LAS bf16x8*)(lds + PG8_SA(b, h) + aoff + m * 2048 + k * 1024); } while (0)
; #define PG8_LDB(dst, b, h) do { _Pragma("unroll") for (int n = 0; n < 2; ++n) _Pragma("unroll") for (int k = 0; k < 2; ++k) dst[n][k] = *(const LAS bf16x8*)(lds + PG8_SB(b, h) + boff + n * 2048 + k * 1024); } while (0)
; #define PG8_WAIT_V(n) asm volatile("s_waitcnt vmcnt(" #n ")" ::: "memory")
; #define PG8_BAR __builtin_amdgcn_s_barrier()
; template <class Epi, class Sched>
; __device__ __forceinline__ void gemm_phase(LAS unsigned char* lds, const Gemm g, const Sched S, const Epi E, const int tid) {
;     ...
;         for (int t = 0; t < nt; t += 2) {
;             const bool last = (t == nt - 2);
;             const char* a1 = cA + (size_t)(t + 1) * kstep;
;             const char* a2 = last ? nA : cA + (size_t)(t + 2) * kstep; const char* b2 = last ? nB : cB + (size_t)(t + 2) * kstep;
;             const char* a3 = a2 + kstep; const char* b3 = b2 + kstep;
;             PG8_LDB(B0, 0, 0); PG8_LDB(B1, 0, 1); PG8_SCHED; PG8_LDA(At, 0, 0); PG8_STAGE(PG8_SA(1, 1), a1 + hstepA, voffA);
;             PG8_WAIT_V(8); PG8_WAIT_L(0); PG8_BAR; PG8_MMA(0, 0, At, B0); PG8_MMA(0, 1, At, B1); PG8_BAR; PG8_SCHED;
;             PG8_LDA(At, 0, 1); PG8_STAGE(PG8_SB(0, 0), b2, voffB); PG8_STAGE(PG8_SB(0, 1), b2 + hstepB, voffB); PG8_STAGE(PG8_SA(0, 0), a2, voffA);
;             PG8_WAIT_V(8); PG8_WAIT_L(0); PG8_BAR; PG8_MMA(1, 0, At, B0); PG8_MMA(1, 1, At, B1); PG8_BAR; PG8_SCHED;
;             PG8_LDB(B0, 1, 0); PG8_LDB(B1, 1, 1); PG8_SCHED; PG8_LDA(At, 1, 0); PG8_STAGE(PG8_SA(0, 1), a2 + hstepA, voffA);
;             PG8_WAIT_V(8); PG8_WAIT_L(0); PG8_BAR; PG8_MMA(0, 0, At, B0); PG8_MMA(0, 1, At, B1); PG8_BAR; PG8_SCHED;
;             PG8_LDA(At, 1, 1); PG8_STAGE(PG8_SB(1, 0), b3, voffB); PG8_STAGE(PG8_SB(1, 1), b3 + hstepB, voffB); PG8_STAGE(PG8_SA(1, 0), a3, voffA);
;             PG8_WAIT_V(8); PG8_WAIT_L(0); PG8_BAR; PG8_MMA(1, 0, At, B0); PG8_MMA(1, 1, At, B1); PG8_BAR; PG8_SCHED;
;         }
.LBB0_310:
	s_mov_b32 s6, s92
	s_ashr_i32 s92, s89, 4
	s_cmp_lt_i32 s89, 32
	s_mov_b64 s[42:43], s[4:5]
	s_cselect_b64 s[4:5], -1, 0
	s_and_b64 s[4:5], s[4:5], exec
	s_cselect_b32 s4, s92, s6
	s_ashr_i32 s5, s4, 31
	s_lshl_b64 s[4:5], s[4:5], 17
	s_add_u32 s4, s25, s4
	s_addc_u32 s5, s46, s5
	s_cmp_lt_i32 s89, 32
	s_cselect_b64 s[10:11], -1, 0
	s_and_b64 s[10:11], s[10:11], exec
	s_cselect_b32 s10, s89, s93
	v_add_u32_e32 v130, s44, v70
	s_cselect_b32 s26, s4, s42
	s_cselect_b32 s27, s5, s43
	s_ashr_i32 s11, s10, 31
	ds_read_b128 v[2:5], v130
	ds_read_b128 v[6:9], v130 offset:1024
	ds_read_b128 v[10:13], v130 offset:2048
	ds_read_b128 v[14:17], v130 offset:3072
	s_lshl_b64 s[10:11], s[10:11], 17
	s_mov_b64 s[40:41], s[16:17]
	s_add_u32 s16, s8, s10
	s_addc_u32 s17, s9, s11
	s_cmp_lt_i32 s89, 32
	s_cselect_b64 s[22:23], -1, 0
	s_and_b64 s[10:11], s[22:23], exec
	s_cselect_b32 s29, s17, s41
	s_cselect_b32 s28, s16, s40
	s_add_u32 s10, s40, 0x10080
	s_addc_u32 s11, s41, 0
	s_add_i32 s97, s37, 0xc000
	v_lshl_add_u64 v[50:51], s[10:11], 0, v[68:69]
	s_mov_b32 m0, s97
	s_add_i32 s13, s37, 0xe000
	ds_read_b128 v[18:21], v71
	ds_read_b128 v[22:25], v71 offset:1024
	ds_read_b128 v[26:29], v71 offset:2048
	ds_read_b128 v[30:33], v71 offset:3072
	ds_read_b128 v[34:37], v71 offset:4096
	ds_read_b128 v[38:41], v71 offset:5120
	ds_read_b128 v[42:45], v71 offset:6144
	ds_read_b128 v[46:49], v71 offset:7168
	global_load_lds_dwordx4 v[50:51], off
	v_lshl_add_u64 v[50:51], s[10:11], 0, v[66:67]
	s_mov_b32 m0, s13
	s_nop 0
	global_load_lds_dwordx4 v[50:51], off
	s_waitcnt vmcnt(8)
	s_waitcnt lgkmcnt(0)
	s_barrier
	s_setprio 1
	s_waitcnt lgkmcnt(0)
	v_mfma_f32_16x16x32_bf16 v[50:53], v[2:5], v[18:21], 0
	v_mfma_f32_16x16x32_bf16 v[18:21], v[10:13], v[18:21], 0
	v_mfma_f32_16x16x32_bf16 v[50:53], v[6:9], v[22:25], v[50:53]
	v_mfma_f32_16x16x32_bf16 v[18:21], v[14:17], v[22:25], v[18:21]
	v_mfma_f32_16x16x32_bf16 v[22:25], v[2:5], v[26:29], 0
	v_mfma_f32_16x16x32_bf16 v[26:29], v[10:13], v[26:29], 0
	v_mfma_f32_16x16x32_bf16 v[22:25], v[6:9], v[30:33], v[22:25]
	v_mfma_f32_16x16x32_bf16 v[26:29], v[14:17], v[30:33], v[26:29]
	v_mfma_f32_16x16x32_bf16 v[30:33], v[2:5], v[34:37], 0
	v_mfma_f32_16x16x32_bf16 v[34:37], v[10:13], v[34:37], 0
	v_mfma_f32_16x16x32_bf16 v[30:33], v[6:9], v[38:41], v[30:33]
	v_mfma_f32_16x16x32_bf16 v[34:37], v[14:17], v[38:41], v[34:37]
	v_mfma_f32_16x16x32_bf16 v[38:41], v[2:5], v[42:45], 0
	v_mfma_f32_16x16x32_bf16 v[42:45], v[10:13], v[42:45], 0
	v_mfma_f32_16x16x32_bf16 v[38:41], v[6:9], v[46:49], v[38:41]
	v_mfma_f32_16x16x32_bf16 v[42:45], v[14:17], v[46:49], v[42:45]
	s_setprio 0
	s_barrier
	s_add_i32 s96, s44, s47
	v_lshl_add_u64 v[120:121], s[42:43], 0, v[68:69]
	s_mov_b64 s[6:7], 0x100
	s_add_i32 s94, s96, 0x2000
	v_lshl_add_u64 v[88:89], v[120:121], 0, s[6:7]
	s_mov_b32 m0, s96
	v_lshl_add_u64 v[122:123], s[42:43], 0, v[66:67]
	s_add_u32 s10, s42, 0x10100
	ds_read_b128 v[46:49], v71 offset:16384
	ds_read_b128 v[54:57], v71 offset:17408
	ds_read_b128 v[58:61], v71 offset:18432
	ds_read_b128 v[62:65], v71 offset:19456
	ds_read_b128 v[72:75], v71 offset:20480
	ds_read_b128 v[76:79], v71 offset:21504
	ds_read_b128 v[80:83], v71 offset:22528
	ds_read_b128 v[84:87], v71 offset:23552
	global_load_lds_dwordx4 v[88:89], off
	v_lshl_add_u64 v[88:89], v[122:123], 0, s[6:7]
	s_mov_b32 m0, s94
	s_addc_u32 s11, s43, 0
	global_load_lds_dwordx4 v[88:89], off
	v_lshl_add_u64 v[88:89], s[10:11], 0, v[68:69]
	s_mov_b32 m0, s48
	v_lshl_add_u64 v[124:125], s[40:41], 0, v[68:69]
	global_load_lds_dwordx4 v[88:89], off
	v_lshl_add_u64 v[88:89], s[10:11], 0, v[66:67]
	s_mov_b32 m0, s49
	v_lshl_add_u64 v[126:127], s[40:41], 0, v[66:67]
	global_load_lds_dwordx4 v[88:89], off
	v_lshl_add_u64 v[88:89], v[124:125], 0, s[6:7]
	s_mov_b32 m0, s37
	s_nop 0
	global_load_lds_dwordx4 v[88:89], off
	v_lshl_add_u64 v[88:89], v[126:127], 0, s[6:7]
	s_mov_b32 m0, s62
	s_nop 0
	global_load_lds_dwordx4 v[88:89], off
	s_waitcnt vmcnt(8)
	s_waitcnt lgkmcnt(0)
	s_barrier
	s_setprio 1
	s_waitcnt lgkmcnt(0)
	v_mfma_f32_16x16x32_bf16 v[88:91], v[2:5], v[46:49], 0
	v_mfma_f32_16x16x32_bf16 v[46:49], v[10:13], v[46:49], 0
	v_mfma_f32_16x16x32_bf16 v[88:91], v[6:9], v[54:57], v[88:91]
	v_mfma_f32_16x16x32_bf16 v[46:49], v[14:17], v[54:57], v[46:49]
	v_mfma_f32_16x16x32_bf16 v[54:57], v[2:5], v[58:61], 0
	v_mfma_f32_16x16x32_bf16 v[58:61], v[10:13], v[58:61], 0
	v_mfma_f32_16x16x32_bf16 v[54:57], v[6:9], v[62:65], v[54:57]
	v_mfma_f32_16x16x32_bf16 v[58:61], v[14:17], v[62:65], v[58:61]
	v_mfma_f32_16x16x32_bf16 v[62:65], v[2:5], v[72:75], 0
	v_mfma_f32_16x16x32_bf16 v[2:5], v[2:5], v[80:83], 0
	v_mfma_f32_16x16x32_bf16 v[62:65], v[6:9], v[76:79], v[62:65]
	v_mfma_f32_16x16x32_bf16 v[2:5], v[6:9], v[84:87], v[2:5]
	v_mfma_f32_16x16x32_bf16 v[6:9], v[10:13], v[80:83], 0
	v_mfma_f32_16x16x32_bf16 v[72:75], v[10:13], v[72:75], 0
	v_mfma_f32_16x16x32_bf16 v[6:9], v[14:17], v[84:87], v[6:9]
	v_mfma_f32_16x16x32_bf16 v[72:75], v[14:17], v[76:79], v[72:75]
	s_setprio 0
	s_barrier
	v_add_u32_e32 v131, s45, v70
	ds_read_b128 v[10:13], v131
	ds_read_b128 v[14:17], v131 offset:1024
	ds_read_b128 v[76:79], v131 offset:2048
	ds_read_b128 v[80:83], v131 offset:3072
	s_add_u32 s10, s40, 0x10100
	s_addc_u32 s11, s41, 0
	s_mov_b32 m0, s68
	v_lshl_add_u64 v[128:129], s[10:11], 0, v[68:69]
	ds_read_b128 v[84:87], v71 offset:32768
	ds_read_b128 v[92:95], v71 offset:33792
	ds_read_b128 v[96:99], v71 offset:34816
	ds_read_b128 v[100:103], v71 offset:35840
	ds_read_b128 v[104:107], v71 offset:36864
	ds_read_b128 v[108:111], v71 offset:37888
	ds_read_b128 v[112:115], v71 offset:38912
	ds_read_b128 v[116:119], v71 offset:39936
	global_load_lds_dwordx4 v[128:129], off
	v_lshl_add_u64 v[128:129], s[10:11], 0, v[66:67]
	s_mov_b32 m0, s69
	s_nop 0
	global_load_lds_dwordx4 v[128:129], off
	s_waitcnt vmcnt(8)
	s_waitcnt lgkmcnt(0)
	s_barrier
; #define PG8_STAGE(bufoff, gbase, voff) do { _Pragma("unroll") for (int _i = 0; _i < 2; ++_i) \
;         __builtin_amdgcn_global_load_lds((const unsigned*)((const char*)(gbase) + (voff)[_i]), (LAS unsigned*)(lds + (bufoff) + ldsw + _i * 8192), 16, 0, 0); } while (0)
; #define PG8_LDA(dst, b, h) do { _Pragma("unroll") for (int m = 0; m < 4; ++m) _Pragma("unroll") for (int k = 0; k < 2; ++k) dst[m][k] = *(const LAS bf16x8*)(lds + PG8_SA(b, h) + aoff + m * 2048 + k * 1024); } while (0)
; #define PG8_LDB(dst, b, h) do { _Pragma("unroll") for (int n = 0; n < 2; ++n) _Pragma("unroll") for (int k = 0; k < 2; ++k) dst[n][k] = *(const LAS bf16x8*)(lds + PG8_SB(b, h) + boff + n * 2048 + k * 1024); } while (0)
; #define PG8_WAIT_V(n) asm volatile("s_waitcnt vmcnt(" #n ")" ::: "memory")
; #define PG8_BAR __builtin_amdgcn_s_barrier()
; template <class Epi, class Sched>
; __device__ __forceinline__ void gemm_phase(LAS unsigned char* lds, const Gemm g, const Sched S, const Epi E, const int tid) {
;     ...
;         for (int t = 0; t < nt; t += 2) {
;             const bool last = (t == nt - 2);
;             const char* a1 = cA + (size_t)(t + 1) * kstep;
;             const char* a2 = last ? nA : cA + (size_t)(t + 2) * kstep; const char* b2 = last ? nB : cB + (size_t)(t + 2) * kstep;
;             const char* a3 = a2 + kstep; const char* b3 = b2 + kstep;
;             PG8_LDB(B0, 0, 0); PG8_LDB(B1, 0, 1); PG8_SCHED; PG8_LDA(At, 0, 0); PG8_STAGE(PG8_SA(1, 1), a1 + hstepA, voffA);
;             PG8_WAIT_V(8); PG8_WAIT_L(0); PG8_BAR; PG8_MMA(0, 0, At, B0); PG8_MMA(0, 1, At, B1); PG8_BAR; PG8_SCHED;
;             PG8_LDA(At, 0, 1); PG8_STAGE(PG8_SB(0, 0), b2, voffB); PG8_STAGE(PG8_SB(0, 1), b2 + hstepB, voffB); PG8_STAGE(PG8_SA(0, 0), a2, voffA);
;             PG8_WAIT_V(8); PG8_WAIT_L(0); PG8_BAR; PG8_MMA(1, 0, At, B0); PG8_MMA(1, 1, At, B1); PG8_BAR; PG8_SCHED;
;             PG8_LDB(B0, 1, 0); PG8_LDB(B1, 1, 1); PG8_SCHED; PG8_LDA(At, 1, 0); PG8_STAGE(PG8_SA(0, 1), a2 + hstepA, voffA);
;             PG8_WAIT_V(8); PG8_WAIT_L(0); PG8_BAR; PG8_MMA(0, 0, At, B0); PG8_MMA(0, 1, At, B1); PG8_BAR; PG8_SCHED;
;             PG8_LDA(At, 1, 1); PG8_STAGE(PG8_SB(1, 0), b3, voffB); PG8_STAGE(PG8_SB(1, 1), b3 + hstepB, voffB); PG8_STAGE(PG8_SA(1, 0), a3, voffA);
;             PG8_WAIT_V(8); PG8_WAIT_L(0); PG8_BAR; PG8_MMA(1, 0, At, B0); PG8_MMA(1, 1, At, B1); PG8_BAR; PG8_SCHED;
;         }
	s_setprio 1
	s_waitcnt lgkmcnt(0)
	v_mfma_f32_16x16x32_bf16 v[50:53], v[10:13], v[84:87], v[50:53]
	v_mfma_f32_16x16x32_bf16 v[18:21], v[76:79], v[84:87], v[18:21]
	v_mfma_f32_16x16x32_bf16 v[22:25], v[10:13], v[96:99], v[22:25]
	v_mfma_f32_16x16x32_bf16 v[26:29], v[76:79], v[96:99], v[26:29]
	v_mfma_f32_16x16x32_bf16 v[30:33], v[10:13], v[104:107], v[30:33]
	v_mfma_f32_16x16x32_bf16 v[34:37], v[76:79], v[104:107], v[34:37]
	v_mfma_f32_16x16x32_bf16 v[38:41], v[10:13], v[112:115], v[38:41]
	v_mfma_f32_16x16x32_bf16 v[42:45], v[76:79], v[112:115], v[42:45]
	v_mfma_f32_16x16x32_bf16 v[50:53], v[14:17], v[92:95], v[50:53]
	v_mfma_f32_16x16x32_bf16 v[18:21], v[80:83], v[92:95], v[18:21]
	v_mfma_f32_16x16x32_bf16 v[22:25], v[14:17], v[100:103], v[22:25]
	v_mfma_f32_16x16x32_bf16 v[26:29], v[80:83], v[100:103], v[26:29]
	v_mfma_f32_16x16x32_bf16 v[30:33], v[14:17], v[108:111], v[30:33]
	v_mfma_f32_16x16x32_bf16 v[34:37], v[80:83], v[108:111], v[34:37]
	v_mfma_f32_16x16x32_bf16 v[38:41], v[14:17], v[116:119], v[38:41]
	v_mfma_f32_16x16x32_bf16 v[42:45], v[80:83], v[116:119], v[42:45]
	s_setprio 0
	s_barrier
	s_add_i32 vcc_lo, s45, s47
	s_mov_b64 s[6:7], 0x180
	s_add_i32 s95, vcc_lo, 0x2000
	v_lshl_add_u64 v[120:121], v[120:121], 0, s[6:7]
	s_mov_b32 m0, vcc_lo
	s_add_u32 s10, s42, 0x10180
	ds_read_b128 v[84:87], v71 offset:49152
	ds_read_b128 v[92:95], v71 offset:50176
	ds_read_b128 v[96:99], v71 offset:51200
	ds_read_b128 v[100:103], v71 offset:52224
	ds_read_b128 v[104:107], v71 offset:53248
	ds_read_b128 v[108:111], v71 offset:54272
	ds_read_b128 v[112:115], v71 offset:55296
	ds_read_b128 v[116:119], v71 offset:56320
	global_load_lds_dwordx4 v[120:121], off
	v_lshl_add_u64 v[120:121], v[122:123], 0, s[6:7]
	s_mov_b32 m0, s95
	s_addc_u32 s11, s43, 0
	global_load_lds_dwordx4 v[120:121], off
	v_lshl_add_u64 v[120:121], s[10:11], 0, v[68:69]
	s_mov_b32 m0, s85
	s_nop 0
	global_load_lds_dwordx4 v[120:121], off
	v_lshl_add_u64 v[120:121], s[10:11], 0, v[66:67]
	s_mov_b32 m0, s88
	s_nop 0
	global_load_lds_dwordx4 v[120:121], off
	v_lshl_add_u64 v[120:121], v[124:125], 0, s[6:7]
	s_mov_b32 m0, s83
	s_nop 0
	global_load_lds_dwordx4 v[120:121], off
	v_lshl_add_u64 v[120:121], v[126:127], 0, s[6:7]
	s_mov_b32 m0, s84
	s_nop 0
	global_load_lds_dwordx4 v[120:121], off
	s_waitcnt vmcnt(8)
	s_waitcnt lgkmcnt(0)
	s_barrier
	s_setprio 1
	s_waitcnt lgkmcnt(0)
	v_mfma_f32_16x16x32_bf16 v[46:49], v[76:79], v[84:87], v[46:49]
	v_mfma_f32_16x16x32_bf16 v[54:57], v[10:13], v[96:99], v[54:57]
	v_mfma_f32_16x16x32_bf16 v[58:61], v[76:79], v[96:99], v[58:61]
	v_mfma_f32_16x16x32_bf16 v[62:65], v[10:13], v[104:107], v[62:65]
	v_mfma_f32_16x16x32_bf16 v[2:5], v[10:13], v[112:115], v[2:5]
	v_mfma_f32_16x16x32_bf16 v[6:9], v[76:79], v[112:115], v[6:9]
	v_mfma_f32_16x16x32_bf16 v[88:91], v[10:13], v[84:87], v[88:91]
	v_mfma_f32_16x16x32_bf16 v[46:49], v[80:83], v[92:95], v[46:49]
	v_mfma_f32_16x16x32_bf16 v[54:57], v[14:17], v[100:103], v[54:57]
	v_mfma_f32_16x16x32_bf16 v[58:61], v[80:83], v[100:103], v[58:61]
	v_mfma_f32_16x16x32_bf16 v[62:65], v[14:17], v[108:111], v[62:65]
	v_mfma_f32_16x16x32_bf16 v[72:75], v[76:79], v[104:107], v[72:75]
	v_mfma_f32_16x16x32_bf16 v[2:5], v[14:17], v[116:119], v[2:5]
	v_mfma_f32_16x16x32_bf16 v[6:9], v[80:83], v[116:119], v[6:9]
	v_mfma_f32_16x16x32_bf16 v[88:91], v[14:17], v[92:95], v[88:91]
	v_mfma_f32_16x16x32_bf16 v[72:75], v[80:83], v[108:111], v[72:75]
	s_setprio 0
	s_barrier
	ds_read_b128 v[10:13], v130
	ds_read_b128 v[14:17], v130 offset:1024
	ds_read_b128 v[76:79], v130 offset:2048
	ds_read_b128 v[80:83], v130 offset:3072
	s_add_u32 s10, s40, 0x10180
	s_addc_u32 s11, s41, 0
	s_mov_b32 m0, s97
	v_lshl_add_u64 v[120:121], s[10:11], 0, v[68:69]
	ds_read_b128 v[84:87], v71
	ds_read_b128 v[92:95], v71 offset:1024
	ds_read_b128 v[96:99], v71 offset:2048
	ds_read_b128 v[100:103], v71 offset:3072
	ds_read_b128 v[104:107], v71 offset:4096
	ds_read_b128 v[108:111], v71 offset:5120
	ds_read_b128 v[112:115], v71 offset:6144
	ds_read_b128 v[116:119], v71 offset:7168
	global_load_lds_dwordx4 v[120:121], off
	v_lshl_add_u64 v[120:121], s[10:11], 0, v[66:67]
	s_mov_b32 m0, s13
	s_nop 0
	global_load_lds_dwordx4 v[120:121], off
	s_waitcnt vmcnt(8)
	s_waitcnt lgkmcnt(0)
	s_barrier
	s_setprio 1
	s_waitcnt lgkmcnt(0)
	v_mfma_f32_16x16x32_bf16 v[38:41], v[10:13], v[112:115], v[38:41]
	v_mfma_f32_16x16x32_bf16 v[50:53], v[10:13], v[84:87], v[50:53]
	v_mfma_f32_16x16x32_bf16 v[18:21], v[76:79], v[84:87], v[18:21]
	v_mfma_f32_16x16x32_bf16 v[22:25], v[10:13], v[96:99], v[22:25]
	v_mfma_f32_16x16x32_bf16 v[26:29], v[76:79], v[96:99], v[26:29]
	v_mfma_f32_16x16x32_bf16 v[30:33], v[10:13], v[104:107], v[30:33]
	v_mfma_f32_16x16x32_bf16 v[34:37], v[76:79], v[104:107], v[34:37]
	v_mfma_f32_16x16x32_bf16 v[84:87], v[14:17], v[116:119], v[38:41]
	v_mfma_f32_16x16x32_bf16 v[38:41], v[76:79], v[112:115], v[42:45]
	v_mfma_f32_16x16x32_bf16 v[50:53], v[14:17], v[92:95], v[50:53]
	v_mfma_f32_16x16x32_bf16 v[18:21], v[80:83], v[92:95], v[18:21]
	v_mfma_f32_16x16x32_bf16 v[22:25], v[14:17], v[100:103], v[22:25]
	v_mfma_f32_16x16x32_bf16 v[26:29], v[80:83], v[100:103], v[26:29]
	v_mfma_f32_16x16x32_bf16 v[30:33], v[14:17], v[108:111], v[30:33]
	v_mfma_f32_16x16x32_bf16 v[34:37], v[80:83], v[108:111], v[34:37]
	v_mfma_f32_16x16x32_bf16 v[42:45], v[80:83], v[116:119], v[38:41]
	s_setprio 0
	s_barrier
; #define PG8_STAGE(bufoff, gbase, voff) do { _Pragma("unroll") for (int _i = 0; _i < 2; ++_i) \
;         __builtin_amdgcn_global_load_lds((const unsigned*)((const char*)(gbase) + (voff)[_i]), (LAS unsigned*)(lds + (bufoff) + ldsw + _i * 8192), 16, 0, 0); } while (0)
; #define PG8_LDA(dst, b, h) do { _Pragma("unroll") for (int m = 0; m < 4; ++m) _Pragma("unroll") for (int k = 0; k < 2; ++k) dst[m][k] = *(const LAS bf16x8*)(lds + PG8_SA(b, h) + aoff + m * 2048 + k * 1024); } while (0)
; #define PG8_LDB(dst, b, h) do { _Pragma("unroll") for (int n = 0; n < 2; ++n) _Pragma("unroll") for (int k = 0; k < 2; ++k) dst[n][k] = *(const LAS bf16x8*)(lds + PG8_SB(b, h) + boff + n * 2048 + k * 1024); } while (0)
; #define PG8_WAIT_V(n) asm volatile("s_waitcnt vmcnt(" #n ")" ::: "memory")
; #define PG8_BAR __builtin_amdgcn_s_barrier()
; template <class Epi, class Sched>
; __device__ __forceinline__ void gemm_phase(LAS unsigned char* lds, const Gemm g, const Sched S, const Epi E, const int tid) {
;     ...
;         for (int t = 0; t < nt; t += 2) {
;             const bool last = (t == nt - 2);
;             const char* a1 = cA + (size_t)(t + 1) * kstep;
;             const char* a2 = last ? nA : cA + (size_t)(t + 2) * kstep; const char* b2 = last ? nB : cB + (size_t)(t + 2) * kstep;
;             const char* a3 = a2 + kstep; const char* b3 = b2 + kstep;
;             PG8_LDB(B0, 0, 0); PG8_LDB(B1, 0, 1); PG8_SCHED; PG8_LDA(At, 0, 0); PG8_STAGE(PG8_SA(1, 1), a1 + hstepA, voffA);
;             PG8_WAIT_V(8); PG8_WAIT_L(0); PG8_BAR; PG8_MMA(0, 0, At, B0); PG8_MMA(0, 1, At, B1); PG8_BAR; PG8_SCHED;
;             PG8_LDA(At, 0, 1); PG8_STAGE(PG8_SB(0, 0), b2, voffB); PG8_STAGE(PG8_SB(0, 1), b2 + hstepB, voffB); PG8_STAGE(PG8_SA(0, 0), a2, voffA);
;             PG8_WAIT_V(8); PG8_WAIT_L(0); PG8_BAR; PG8_MMA(1, 0, At, B0); PG8_MMA(1, 1, At, B1); PG8_BAR; PG8_SCHED;
;             PG8_LDB(B0, 1, 0); PG8_LDB(B1, 1, 1); PG8_SCHED; PG8_LDA(At, 1, 0); PG8_STAGE(PG8_SA(0, 1), a2 + hstepA, voffA);
;             PG8_WAIT_V(8); PG8_WAIT_L(0); PG8_BAR; PG8_MMA(0, 0, At, B0); PG8_MMA(0, 1, At, B1); PG8_BAR; PG8_SCHED;
;             PG8_LDA(At, 1, 1); PG8_STAGE(PG8_SB(1, 0), b3, voffB); PG8_STAGE(PG8_SB(1, 1), b3 + hstepB, voffB); PG8_STAGE(PG8_SA(1, 0), a3, voffA);
;             PG8_WAIT_V(8); PG8_WAIT_L(0); PG8_BAR; PG8_MMA(1, 0, At, B0); PG8_MMA(1, 1, At, B1); PG8_BAR; PG8_SCHED;
;         }
	s_mov_b32 m0, s96
	v_lshl_add_u64 v[132:133], s[26:27], 0, v[68:69]
	s_add_u32 s10, s26, 0x10000
	ds_read_b128 v[38:41], v71 offset:16384
	ds_read_b128 v[92:95], v71 offset:17408
	ds_read_b128 v[96:99], v71 offset:18432
	ds_read_b128 v[100:103], v71 offset:19456
	ds_read_b128 v[104:107], v71 offset:20480
	ds_read_b128 v[108:111], v71 offset:21504
	ds_read_b128 v[112:115], v71 offset:22528
	ds_read_b128 v[116:119], v71 offset:23552
	global_load_lds_dwordx4 v[132:133], off
	v_lshl_add_u64 v[134:135], s[26:27], 0, v[66:67]
	s_mov_b32 m0, s94
	s_addc_u32 s11, s27, 0
	global_load_lds_dwordx4 v[134:135], off
	v_lshl_add_u64 v[120:121], s[10:11], 0, v[68:69]
	s_mov_b32 m0, s48
	v_lshl_add_u64 v[136:137], s[28:29], 0, v[68:69]
	global_load_lds_dwordx4 v[120:121], off
	v_lshl_add_u64 v[120:121], s[10:11], 0, v[66:67]
	s_mov_b32 m0, s49
	v_lshl_add_u64 v[138:139], s[28:29], 0, v[66:67]
	global_load_lds_dwordx4 v[120:121], off
	s_mov_b32 m0, s37
	s_nop 0
	global_load_lds_dwordx4 v[136:137], off
	s_mov_b32 m0, s62
	s_nop 0
	global_load_lds_dwordx4 v[138:139], off
	s_waitcnt vmcnt(8)
	s_waitcnt lgkmcnt(0)
	s_barrier
	s_setprio 1
	s_waitcnt lgkmcnt(0)
	v_mfma_f32_16x16x32_bf16 v[88:91], v[10:13], v[38:41], v[88:91]
	v_mfma_f32_16x16x32_bf16 v[38:41], v[76:79], v[38:41], v[46:49]
	v_mfma_f32_16x16x32_bf16 v[88:91], v[14:17], v[92:95], v[88:91]
	v_mfma_f32_16x16x32_bf16 v[92:95], v[80:83], v[92:95], v[38:41]
	v_mfma_f32_16x16x32_bf16 v[38:41], v[10:13], v[96:99], v[54:57]
	v_mfma_f32_16x16x32_bf16 v[120:123], v[14:17], v[100:103], v[38:41]
	v_mfma_f32_16x16x32_bf16 v[38:41], v[76:79], v[96:99], v[58:61]
	v_mfma_f32_16x16x32_bf16 v[96:99], v[80:83], v[100:103], v[38:41]
	v_mfma_f32_16x16x32_bf16 v[38:41], v[10:13], v[104:107], v[62:65]
	v_mfma_f32_16x16x32_bf16 v[2:5], v[10:13], v[112:115], v[2:5]
	v_mfma_f32_16x16x32_bf16 v[100:103], v[14:17], v[108:111], v[38:41]
	v_mfma_f32_16x16x32_bf16 v[38:41], v[76:79], v[104:107], v[72:75]
	v_mfma_f32_16x16x32_bf16 v[2:5], v[14:17], v[116:119], v[2:5]
	v_mfma_f32_16x16x32_bf16 v[6:9], v[76:79], v[112:115], v[6:9]
	v_mfma_f32_16x16x32_bf16 v[72:75], v[80:83], v[108:111], v[38:41]
	v_mfma_f32_16x16x32_bf16 v[76:79], v[80:83], v[116:119], v[6:9]
	s_setprio 0
	s_barrier
	s_nop 1
	ds_read_b128 v[6:9], v131
	ds_read_b128 v[80:83], v131 offset:1024
	ds_read_b128 v[104:107], v131 offset:2048
	ds_read_b128 v[108:111], v131 offset:3072
	s_add_u32 s10, s28, 0x10000
	s_addc_u32 s11, s29, 0
	s_mov_b32 m0, s68
	v_lshl_add_u64 v[54:55], s[10:11], 0, v[68:69]
	ds_read_b128 v[10:13], v71 offset:32768
	ds_read_b128 v[14:17], v71 offset:33792
	ds_read_b128 v[38:41], v71 offset:34816
	ds_read_b128 v[46:49], v71 offset:35840
	ds_read_b128 v[112:115], v71 offset:36864
	ds_read_b128 v[116:119], v71 offset:37888
	ds_read_b128 v[124:127], v71 offset:38912
	ds_read_b128 v[128:131], v71 offset:39936
	global_load_lds_dwordx4 v[54:55], off
	v_lshl_add_u64 v[54:55], s[10:11], 0, v[66:67]
	s_mov_b32 m0, s69
	s_nop 0
	global_load_lds_dwordx4 v[54:55], off
	s_waitcnt vmcnt(8)
	s_waitcnt lgkmcnt(0)
	s_barrier
	s_setprio 1
	s_waitcnt lgkmcnt(0)
	v_mfma_f32_16x16x32_bf16 v[50:53], v[6:9], v[10:13], v[50:53]
	v_mfma_f32_16x16x32_bf16 v[10:13], v[104:107], v[10:13], v[18:21]
	v_mfma_f32_16x16x32_bf16 v[58:61], v[108:111], v[14:17], v[10:13]
	v_mfma_f32_16x16x32_bf16 v[10:13], v[6:9], v[38:41], v[22:25]
	v_mfma_f32_16x16x32_bf16 v[54:57], v[80:83], v[46:49], v[10:13]
	v_mfma_f32_16x16x32_bf16 v[10:13], v[104:107], v[38:41], v[26:29]
	v_mfma_f32_16x16x32_bf16 v[62:65], v[80:83], v[14:17], v[50:53]
	v_mfma_f32_16x16x32_bf16 v[50:53], v[108:111], v[46:49], v[10:13]
	v_mfma_f32_16x16x32_bf16 v[10:13], v[6:9], v[112:115], v[30:33]
	v_mfma_f32_16x16x32_bf16 v[46:49], v[80:83], v[116:119], v[10:13]
	v_mfma_f32_16x16x32_bf16 v[10:13], v[104:107], v[112:115], v[34:37]
	v_mfma_f32_16x16x32_bf16 v[38:41], v[108:111], v[116:119], v[10:13]
	v_mfma_f32_16x16x32_bf16 v[10:13], v[6:9], v[124:127], v[84:87]
	v_mfma_f32_16x16x32_bf16 v[30:33], v[80:83], v[128:131], v[10:13]
	v_mfma_f32_16x16x32_bf16 v[10:13], v[104:107], v[124:127], v[42:45]
	v_mfma_f32_16x16x32_bf16 v[22:25], v[108:111], v[128:131], v[10:13]
	s_setprio 0
	s_barrier
	s_mov_b32 m0, vcc_lo
	v_lshl_add_u64 v[26:27], v[132:133], 0, s[64:65]
	s_add_u32 s10, s26, 0x10080
	ds_read_b128 v[10:13], v71 offset:49152
	ds_read_b128 v[14:17], v71 offset:50176
	ds_read_b128 v[18:21], v71 offset:51200
	ds_read_b128 v[84:87], v71 offset:52224
	ds_read_b128 v[112:115], v71 offset:53248
	ds_read_b128 v[116:119], v71 offset:54272
	ds_read_b128 v[124:127], v71 offset:55296
	ds_read_b128 v[128:131], v71 offset:56320
	global_load_lds_dwordx4 v[26:27], off
	v_lshl_add_u64 v[26:27], v[134:135], 0, s[64:65]
	s_mov_b32 m0, s95
	s_addc_u32 s11, s27, 0
	global_load_lds_dwordx4 v[26:27], off
	v_lshl_add_u64 v[26:27], s[10:11], 0, v[68:69]
	s_mov_b32 m0, s85
	s_nop 0
	global_load_lds_dwordx4 v[26:27], off
	v_lshl_add_u64 v[26:27], s[10:11], 0, v[66:67]
	s_mov_b32 m0, s88
	s_nop 0
	global_load_lds_dwordx4 v[26:27], off
	v_lshl_add_u64 v[26:27], v[136:137], 0, s[64:65]
	s_mov_b32 m0, s83
	s_nop 0
	global_load_lds_dwordx4 v[26:27], off
	v_lshl_add_u64 v[26:27], v[138:139], 0, s[64:65]
	s_mov_b32 m0, s84
	s_nop 0
	global_load_lds_dwordx4 v[26:27], off
	s_waitcnt vmcnt(8)
	s_waitcnt lgkmcnt(0)
	s_barrier
	s_setprio 1
	s_waitcnt lgkmcnt(0)
	v_mfma_f32_16x16x32_bf16 v[26:29], v[6:9], v[10:13], v[88:91]
	v_mfma_f32_16x16x32_bf16 v[10:13], v[104:107], v[10:13], v[92:95]
	v_mfma_f32_16x16x32_bf16 v[34:37], v[108:111], v[14:17], v[10:13]
	v_mfma_f32_16x16x32_bf16 v[10:13], v[6:9], v[18:21], v[120:123]
	v_mfma_f32_16x16x32_bf16 v[42:45], v[80:83], v[14:17], v[26:29]
	v_mfma_f32_16x16x32_bf16 v[26:29], v[80:83], v[84:87], v[10:13]
	v_mfma_f32_16x16x32_bf16 v[10:13], v[104:107], v[18:21], v[96:99]
	v_mfma_f32_16x16x32_bf16 v[18:21], v[108:111], v[84:87], v[10:13]
	v_mfma_f32_16x16x32_bf16 v[10:13], v[6:9], v[112:115], v[100:103]
	v_mfma_f32_16x16x32_bf16 v[2:5], v[6:9], v[124:127], v[2:5]
	v_mfma_f32_16x16x32_bf16 v[14:17], v[80:83], v[116:119], v[10:13]
	v_mfma_f32_16x16x32_bf16 v[10:13], v[104:107], v[112:115], v[72:75]
	v_mfma_f32_16x16x32_bf16 v[6:9], v[80:83], v[128:131], v[2:5]
	v_mfma_f32_16x16x32_bf16 v[2:5], v[104:107], v[124:127], v[76:79]
	v_mfma_f32_16x16x32_bf16 v[10:13], v[108:111], v[116:119], v[10:13]
	v_mfma_f32_16x16x32_bf16 v[2:5], v[108:111], v[128:131], v[2:5]
	s_setprio 0
	s_barrier
	s_andn2_b64 vcc, exec, s[18:19]
	s_cbranch_vccnz .LBB0_312
	s_barrier

; #define PG8_STAGE(bufoff, gbase, voff) do { _Pragma("unroll") for (int _i = 0; _i < 2; ++_i) \
;         __builtin_amdgcn_global_load_lds((const unsigned*)((const char*)(gbase) + (voff)[_i]), (LAS unsigned*)(lds + (bufoff) + ldsw + _i * 8192), 16, 0, 0); } while (0)
; #define PG8_LDA(dst, b, h) do { _Pragma("unroll") for (int m = 0; m < 4; ++m) _Pragma("unroll") for (int k = 0; k < 2; ++k) dst[m][k] = *(const LAS bf16x8*)(lds + PG8_SA(b, h) + aoff + m * 2048 + k * 1024); } while (0)
; #define PG8_LDB(dst, b, h) do { _Pragma("unroll") for (int n = 0; n < 2; ++n) _Pragma("unroll") for (int k = 0; k < 2; ++k) dst[n][k] = *(const LAS bf16x8*)(lds + PG8_SB(b, h) + boff + n * 2048 + k * 1024); } while (0)
; #define PG8_WAIT_V(n) asm volatile("s_waitcnt vmcnt(" #n ")" ::: "memory")
; #define PG8_BAR __builtin_amdgcn_s_barrier()
; template <class Epi, class Sched>
; __device__ __forceinline__ void gemm_phase(LAS unsigned char* lds, const Gemm g, const Sched S, const Epi E, const int tid) {
;     ...
;         for (int t = 0; t < nt; t += 2) {
;             const bool last = (t == nt - 2);
;             const char* a1 = cA + (size_t)(t + 1) * kstep;
;             const char* a2 = last ? nA : cA + (size_t)(t + 2) * kstep; const char* b2 = last ? nB : cB + (size_t)(t + 2) * kstep;
;             const char* a3 = a2 + kstep; const char* b3 = b2 + kstep;
;             PG8_LDB(B0, 0, 0); PG8_LDB(B1, 0, 1); PG8_SCHED; PG8_LDA(At, 0, 0); PG8_STAGE(PG8_SA(1, 1), a1 + hstepA, voffA);
;             PG8_WAIT_V(8); PG8_WAIT_L(0); PG8_BAR; PG8_MMA(0, 0, At, B0); PG8_MMA(0, 1, At, B1); PG8_BAR; PG8_SCHED;
;             PG8_LDA(At, 0, 1); PG8_STAGE(PG8_SB(0, 0), b2, voffB); PG8_STAGE(PG8_SB(0, 1), b2 + hstepB, voffB); PG8_STAGE(PG8_SA(0, 0), a2, voffA);
;             PG8_WAIT_V(8); PG8_WAIT_L(0); PG8_BAR; PG8_MMA(1, 0, At, B0); PG8_MMA(1, 1, At, B1); PG8_BAR; PG8_SCHED;
;             PG8_LDB(B0, 1, 0); PG8_LDB(B1, 1, 1); PG8_SCHED; PG8_LDA(At, 1, 0); PG8_STAGE(PG8_SA(0, 1), a2 + hstepA, voffA);
;             PG8_WAIT_V(8); PG8_WAIT_L(0); PG8_BAR; PG8_MMA(0, 0, At, B0); PG8_MMA(0, 1, At, B1); PG8_BAR; PG8_SCHED;
;             PG8_LDA(At, 1, 1); PG8_STAGE(PG8_SB(1, 0), b3, voffB); PG8_STAGE(PG8_SB(1, 1), b3 + hstepB, voffB); PG8_STAGE(PG8_SA(1, 0), a3, voffA);
;             PG8_WAIT_V(8); PG8_WAIT_L(0); PG8_BAR; PG8_MMA(1, 0, At, B0); PG8_MMA(1, 1, At, B1); PG8_BAR; PG8_SCHED;
;         }
.LBB0_332:
	s_add_u32 s10, s44, 0xfffc0080
	s_addc_u32 s11, s45, -1
	s_add_i32 vcc_lo, 0, 0x10000
	s_cmp_eq_u32 s97, 12
	s_cselect_b32 s83, s7, s11
	s_cselect_b32 s82, s92, s10
	v_add_u32_e32 v154, vcc_lo, v157
	s_cselect_b32 s47, s93, s96
	s_cselect_b32 s46, s94, s95
	s_add_i32 vcc_hi, 0, 0x14000
	s_waitcnt lgkmcnt(0)
	ds_read_b128 v[130:133], v154
	ds_read_b128 v[134:137], v154 offset:1024
	ds_read_b128 v[150:153], v154 offset:2048
	ds_read_b128 v[160:163], v154 offset:3072
	v_add_u32_e32 v154, vcc_hi, v157
	ds_read_b128 v[164:167], v154
	ds_read_b128 v[180:183], v154 offset:1024
	ds_read_b128 v[184:187], v154 offset:2048
	ds_read_b128 v[188:191], v154 offset:3072
	v_lshl_add_u64 v[154:155], s[44:45], 0, v[148:149]
	s_add_i32 m0, s48, 0xc000
	ds_read_b128 v[192:195], v158
	ds_read_b128 v[196:199], v158 offset:1024
	ds_read_b128 v[200:203], v158 offset:2048
	ds_read_b128 v[204:207], v158 offset:3072
	ds_read_b128 v[208:211], v158 offset:4096
	ds_read_b128 v[212:215], v158 offset:5120
	ds_read_b128 v[216:219], v158 offset:6144
	ds_read_b128 v[220:223], v158 offset:7168
	global_load_lds_dwordx4 v[154:155], off
	v_lshl_add_u64 v[154:155], s[44:45], 0, v[146:147]
	s_add_i32 m0, s48, 0xe000
	s_nop 0
	global_load_lds_dwordx4 v[154:155], off
	s_waitcnt vmcnt(8)
	s_waitcnt lgkmcnt(0)
	s_barrier
	s_setprio 1
	s_waitcnt lgkmcnt(0)
	v_mfma_f32_16x16x32_bf16 v[122:125], v[130:133], v[192:195], v[122:125]
	v_mfma_f32_16x16x32_bf16 v[114:117], v[150:153], v[192:195], v[114:117]
	v_mfma_f32_16x16x32_bf16 v[106:109], v[130:133], v[200:203], v[106:109]
	v_mfma_f32_16x16x32_bf16 v[98:101], v[150:153], v[200:203], v[98:101]
	v_mfma_f32_16x16x32_bf16 v[90:93], v[130:133], v[208:211], v[90:93]
	v_mfma_f32_16x16x32_bf16 v[82:85], v[150:153], v[208:211], v[82:85]
	v_mfma_f32_16x16x32_bf16 v[74:77], v[130:133], v[216:219], v[74:77]
	v_mfma_f32_16x16x32_bf16 v[66:69], v[150:153], v[216:219], v[66:69]
	v_mfma_f32_16x16x32_bf16 v[122:125], v[134:137], v[196:199], v[122:125]
	v_mfma_f32_16x16x32_bf16 v[114:117], v[160:163], v[196:199], v[114:117]
	v_mfma_f32_16x16x32_bf16 v[106:109], v[134:137], v[204:207], v[106:109]
	v_mfma_f32_16x16x32_bf16 v[98:101], v[160:163], v[204:207], v[98:101]
	v_mfma_f32_16x16x32_bf16 v[90:93], v[134:137], v[212:215], v[90:93]
	v_mfma_f32_16x16x32_bf16 v[82:85], v[160:163], v[212:215], v[82:85]
	v_mfma_f32_16x16x32_bf16 v[74:77], v[134:137], v[220:223], v[74:77]
	v_mfma_f32_16x16x32_bf16 v[66:69], v[160:163], v[220:223], v[66:69]
	v_mfma_f32_16x16x32_bf16 v[126:129], v[164:167], v[192:195], v[126:129]
	v_mfma_f32_16x16x32_bf16 v[118:121], v[184:187], v[192:195], v[118:121]
	v_mfma_f32_16x16x32_bf16 v[110:113], v[164:167], v[200:203], v[110:113]
	v_mfma_f32_16x16x32_bf16 v[102:105], v[184:187], v[200:203], v[102:105]
	v_mfma_f32_16x16x32_bf16 v[94:97], v[164:167], v[208:211], v[94:97]
	v_mfma_f32_16x16x32_bf16 v[86:89], v[184:187], v[208:211], v[86:89]
	v_mfma_f32_16x16x32_bf16 v[78:81], v[164:167], v[216:219], v[78:81]
	v_mfma_f32_16x16x32_bf16 v[70:73], v[184:187], v[216:219], v[70:73]
	v_mfma_f32_16x16x32_bf16 v[126:129], v[180:183], v[196:199], v[126:129]
	v_mfma_f32_16x16x32_bf16 v[118:121], v[188:191], v[196:199], v[118:121]
	v_mfma_f32_16x16x32_bf16 v[110:113], v[180:183], v[204:207], v[110:113]
	v_mfma_f32_16x16x32_bf16 v[102:105], v[188:191], v[204:207], v[102:105]
	v_mfma_f32_16x16x32_bf16 v[94:97], v[180:183], v[212:215], v[94:97]
	v_mfma_f32_16x16x32_bf16 v[86:89], v[188:191], v[212:215], v[86:89]
	v_mfma_f32_16x16x32_bf16 v[78:81], v[180:183], v[220:223], v[78:81]
	v_mfma_f32_16x16x32_bf16 v[70:73], v[188:191], v[220:223], v[70:73]
	s_setprio 0
	s_barrier
	s_add_i32 s10, vcc_lo, s37
	v_lshl_add_u64 v[154:155], s[46:47], 0, v[140:141]
	s_mov_b32 m0, s10
	ds_read_b128 v[192:195], v158 offset:16384
	ds_read_b128 v[196:199], v158 offset:17408
	ds_read_b128 v[200:203], v158 offset:18432
	ds_read_b128 v[204:207], v158 offset:19456
	ds_read_b128 v[208:211], v158 offset:20480
	ds_read_b128 v[212:215], v158 offset:21504
	ds_read_b128 v[216:219], v158 offset:22528
	ds_read_b128 v[220:223], v158 offset:23552
	global_load_lds_dwordx4 v[154:155], off
	s_add_i32 m0, s10, 0x2000
	s_add_u32 s10, s46, 0x40000
	v_lshl_add_u64 v[224:225], s[46:47], 0, v[144:145]
	s_addc_u32 s11, s47, 0
	s_add_i32 vcc_lo, vcc_hi, s37
	global_load_lds_dwordx4 v[224:225], off
	v_lshl_add_u64 v[226:227], s[10:11], 0, v[140:141]
	s_mov_b32 m0, vcc_lo
	v_lshl_add_u64 v[228:229], s[82:83], 0, v[142:143]
	global_load_lds_dwordx4 v[226:227], off
	v_lshl_add_u64 v[226:227], s[10:11], 0, v[144:145]
	s_add_i32 m0, vcc_lo, 0x2000
	s_nop 0
	global_load_lds_dwordx4 v[226:227], off
	v_lshl_add_u64 v[226:227], s[82:83], 0, v[138:139]
	s_mov_b32 m0, s48
	s_nop 0
	global_load_lds_dwordx4 v[226:227], off
	s_mov_b32 m0, s49
	s_nop 0
	global_load_lds_dwordx4 v[228:229], off
	s_waitcnt vmcnt(8)
	s_waitcnt lgkmcnt(0)
	s_barrier
; #define PG8_STAGE(bufoff, gbase, voff) do { _Pragma("unroll") for (int _i = 0; _i < 2; ++_i) \
;         __builtin_amdgcn_global_load_lds((const unsigned*)((const char*)(gbase) + (voff)[_i]), (LAS unsigned*)(lds + (bufoff) + ldsw + _i * 8192), 16, 0, 0); } while (0)
; #define PG8_LDA(dst, b, h) do { _Pragma("unroll") for (int m = 0; m < 4; ++m) _Pragma("unroll") for (int k = 0; k < 2; ++k) dst[m][k] = *(const LAS bf16x8*)(lds + PG8_SA(b, h) + aoff + m * 2048 + k * 1024); } while (0)
; #define PG8_LDB(dst, b, h) do { _Pragma("unroll") for (int n = 0; n < 2; ++n) _Pragma("unroll") for (int k = 0; k < 2; ++k) dst[n][k] = *(const LAS bf16x8*)(lds + PG8_SB(b, h) + boff + n * 2048 + k * 1024); } while (0)
; #define PG8_WAIT_V(n) asm volatile("s_waitcnt vmcnt(" #n ")" ::: "memory")
; #define PG8_BAR __builtin_amdgcn_s_barrier()
; template <class Epi, class Sched>
; __device__ __forceinline__ void gemm_phase(LAS unsigned char* lds, const Gemm g, const Sched S, const Epi E, const int tid) {
;     ...
;         for (int t = 0; t < nt; t += 2) {
;             const bool last = (t == nt - 2);
;             const char* a1 = cA + (size_t)(t + 1) * kstep;
;             const char* a2 = last ? nA : cA + (size_t)(t + 2) * kstep; const char* b2 = last ? nB : cB + (size_t)(t + 2) * kstep;
;             const char* a3 = a2 + kstep; const char* b3 = b2 + kstep;
;             PG8_LDB(B0, 0, 0); PG8_LDB(B1, 0, 1); PG8_SCHED; PG8_LDA(At, 0, 0); PG8_STAGE(PG8_SA(1, 1), a1 + hstepA, voffA);
;             PG8_WAIT_V(8); PG8_WAIT_L(0); PG8_BAR; PG8_MMA(0, 0, At, B0); PG8_MMA(0, 1, At, B1); PG8_BAR; PG8_SCHED;
;             PG8_LDA(At, 0, 1); PG8_STAGE(PG8_SB(0, 0), b2, voffB); PG8_STAGE(PG8_SB(0, 1), b2 + hstepB, voffB); PG8_STAGE(PG8_SA(0, 0), a2, voffA);
;             PG8_WAIT_V(8); PG8_WAIT_L(0); PG8_BAR; PG8_MMA(1, 0, At, B0); PG8_MMA(1, 1, At, B1); PG8_BAR; PG8_SCHED;
;             PG8_LDB(B0, 1, 0); PG8_LDB(B1, 1, 1); PG8_SCHED; PG8_LDA(At, 1, 0); PG8_STAGE(PG8_SA(0, 1), a2 + hstepA, voffA);
;             PG8_WAIT_V(8); PG8_WAIT_L(0); PG8_BAR; PG8_MMA(0, 0, At, B0); PG8_MMA(0, 1, At, B1); PG8_BAR; PG8_SCHED;
;             PG8_LDA(At, 1, 1); PG8_STAGE(PG8_SB(1, 0), b3, voffB); PG8_STAGE(PG8_SB(1, 1), b3 + hstepB, voffB); PG8_STAGE(PG8_SA(1, 0), a3, voffA);
;             PG8_WAIT_V(8); PG8_WAIT_L(0); PG8_BAR; PG8_MMA(1, 0, At, B0); PG8_MMA(1, 1, At, B1); PG8_BAR; PG8_SCHED;
;         }
	s_setprio 1
	s_waitcnt lgkmcnt(0)
	v_mfma_f32_16x16x32_bf16 v[58:61], v[130:133], v[192:195], v[58:61]
	v_mfma_f32_16x16x32_bf16 v[50:53], v[150:153], v[192:195], v[50:53]
	v_mfma_f32_16x16x32_bf16 v[42:45], v[130:133], v[200:203], v[42:45]
	v_mfma_f32_16x16x32_bf16 v[34:37], v[150:153], v[200:203], v[34:37]
	v_mfma_f32_16x16x32_bf16 v[26:29], v[130:133], v[208:211], v[26:29]
	v_mfma_f32_16x16x32_bf16 v[18:21], v[150:153], v[208:211], v[18:21]
	v_mfma_f32_16x16x32_bf16 v[10:13], v[130:133], v[216:219], v[10:13]
	v_mfma_f32_16x16x32_bf16 v[6:9], v[150:153], v[216:219], v[6:9]
	v_mfma_f32_16x16x32_bf16 v[58:61], v[134:137], v[196:199], v[58:61]
	v_mfma_f32_16x16x32_bf16 v[50:53], v[160:163], v[196:199], v[50:53]
	v_mfma_f32_16x16x32_bf16 v[42:45], v[134:137], v[204:207], v[42:45]
	v_mfma_f32_16x16x32_bf16 v[34:37], v[160:163], v[204:207], v[34:37]
	v_mfma_f32_16x16x32_bf16 v[26:29], v[134:137], v[212:215], v[26:29]
	v_mfma_f32_16x16x32_bf16 v[18:21], v[160:163], v[212:215], v[18:21]
	v_mfma_f32_16x16x32_bf16 v[10:13], v[134:137], v[220:223], v[10:13]
	v_mfma_f32_16x16x32_bf16 v[6:9], v[160:163], v[220:223], v[6:9]
	v_mfma_f32_16x16x32_bf16 v[62:65], v[164:167], v[192:195], v[62:65]
	v_mfma_f32_16x16x32_bf16 v[54:57], v[184:187], v[192:195], v[54:57]
	v_mfma_f32_16x16x32_bf16 v[46:49], v[164:167], v[200:203], v[46:49]
	v_mfma_f32_16x16x32_bf16 v[38:41], v[184:187], v[200:203], v[38:41]
	v_mfma_f32_16x16x32_bf16 v[30:33], v[164:167], v[208:211], v[30:33]
	v_mfma_f32_16x16x32_bf16 v[22:25], v[184:187], v[208:211], v[22:25]
	v_mfma_f32_16x16x32_bf16 v[14:17], v[164:167], v[216:219], v[14:17]
	v_mfma_f32_16x16x32_bf16 v[2:5], v[184:187], v[216:219], v[2:5]
	v_mfma_f32_16x16x32_bf16 v[62:65], v[180:183], v[196:199], v[62:65]
	v_mfma_f32_16x16x32_bf16 v[54:57], v[188:191], v[196:199], v[54:57]
	v_mfma_f32_16x16x32_bf16 v[46:49], v[180:183], v[204:207], v[46:49]
	v_mfma_f32_16x16x32_bf16 v[38:41], v[188:191], v[204:207], v[38:41]
	v_mfma_f32_16x16x32_bf16 v[30:33], v[180:183], v[212:215], v[30:33]
	v_mfma_f32_16x16x32_bf16 v[22:25], v[188:191], v[212:215], v[22:25]
	v_mfma_f32_16x16x32_bf16 v[14:17], v[180:183], v[220:223], v[14:17]
	v_mfma_f32_16x16x32_bf16 v[2:5], v[188:191], v[220:223], v[2:5]
	s_setprio 0
	s_barrier
	s_add_i32 vcc_lo, 0, 0x18000
	v_add_u32_e32 v159, vcc_lo, v157
	s_add_i32 vcc_hi, 0, 0x1c000
	ds_read_b128 v[130:133], v159
	ds_read_b128 v[134:137], v159 offset:1024
	ds_read_b128 v[150:153], v159 offset:2048
	ds_read_b128 v[160:163], v159 offset:3072
	v_add_u32_e32 v159, vcc_hi, v157
	ds_read_b128 v[164:167], v159
	ds_read_b128 v[180:183], v159 offset:1024
	ds_read_b128 v[184:187], v159 offset:2048
	ds_read_b128 v[188:191], v159 offset:3072
	s_add_u32 s10, s82, 0x40000
	s_addc_u32 s11, s83, 0
	s_mov_b32 m0, s62
	v_lshl_add_u64 v[230:231], s[10:11], 0, v[138:139]
	ds_read_b128 v[192:195], v158 offset:32768
	ds_read_b128 v[196:199], v158 offset:33792
	ds_read_b128 v[200:203], v158 offset:34816
	ds_read_b128 v[204:207], v158 offset:35840
	ds_read_b128 v[208:211], v158 offset:36864
	ds_read_b128 v[212:215], v158 offset:37888
	ds_read_b128 v[216:219], v158 offset:38912
	ds_read_b128 v[220:223], v158 offset:39936
	global_load_lds_dwordx4 v[230:231], off
	v_lshl_add_u64 v[230:231], s[10:11], 0, v[142:143]
	s_mov_b32 m0, s68
	s_nop 0
	global_load_lds_dwordx4 v[230:231], off
	s_waitcnt vmcnt(8)
	s_waitcnt lgkmcnt(0)
	s_barrier
	s_setprio 1
	s_waitcnt lgkmcnt(0)
	v_mfma_f32_16x16x32_bf16 v[122:125], v[130:133], v[192:195], v[122:125]
	v_mfma_f32_16x16x32_bf16 v[114:117], v[150:153], v[192:195], v[114:117]
	v_mfma_f32_16x16x32_bf16 v[106:109], v[130:133], v[200:203], v[106:109]
	v_mfma_f32_16x16x32_bf16 v[98:101], v[150:153], v[200:203], v[98:101]
	v_mfma_f32_16x16x32_bf16 v[90:93], v[130:133], v[208:211], v[90:93]
	v_mfma_f32_16x16x32_bf16 v[82:85], v[150:153], v[208:211], v[82:85]
	v_mfma_f32_16x16x32_bf16 v[74:77], v[130:133], v[216:219], v[74:77]
	v_mfma_f32_16x16x32_bf16 v[66:69], v[150:153], v[216:219], v[66:69]
	v_mfma_f32_16x16x32_bf16 v[122:125], v[134:137], v[196:199], v[122:125]
	v_mfma_f32_16x16x32_bf16 v[114:117], v[160:163], v[196:199], v[114:117]
	v_mfma_f32_16x16x32_bf16 v[106:109], v[134:137], v[204:207], v[106:109]
	v_mfma_f32_16x16x32_bf16 v[98:101], v[160:163], v[204:207], v[98:101]
	v_mfma_f32_16x16x32_bf16 v[90:93], v[134:137], v[212:215], v[90:93]
	v_mfma_f32_16x16x32_bf16 v[82:85], v[160:163], v[212:215], v[82:85]
	v_mfma_f32_16x16x32_bf16 v[74:77], v[134:137], v[220:223], v[74:77]
	v_mfma_f32_16x16x32_bf16 v[66:69], v[160:163], v[220:223], v[66:69]
	v_mfma_f32_16x16x32_bf16 v[126:129], v[164:167], v[192:195], v[126:129]
	v_mfma_f32_16x16x32_bf16 v[118:121], v[184:187], v[192:195], v[118:121]
	v_mfma_f32_16x16x32_bf16 v[110:113], v[164:167], v[200:203], v[110:113]
	v_mfma_f32_16x16x32_bf16 v[102:105], v[184:187], v[200:203], v[102:105]
	v_mfma_f32_16x16x32_bf16 v[94:97], v[164:167], v[208:211], v[94:97]
	v_mfma_f32_16x16x32_bf16 v[86:89], v[184:187], v[208:211], v[86:89]
	v_mfma_f32_16x16x32_bf16 v[78:81], v[164:167], v[216:219], v[78:81]
	v_mfma_f32_16x16x32_bf16 v[70:73], v[184:187], v[216:219], v[70:73]
	v_mfma_f32_16x16x32_bf16 v[126:129], v[180:183], v[196:199], v[126:129]
	v_mfma_f32_16x16x32_bf16 v[118:121], v[188:191], v[196:199], v[118:121]
	v_mfma_f32_16x16x32_bf16 v[110:113], v[180:183], v[204:207], v[110:113]
	v_mfma_f32_16x16x32_bf16 v[102:105], v[188:191], v[204:207], v[102:105]
	v_mfma_f32_16x16x32_bf16 v[94:97], v[180:183], v[212:215], v[94:97]
	v_mfma_f32_16x16x32_bf16 v[86:89], v[188:191], v[212:215], v[86:89]
	v_mfma_f32_16x16x32_bf16 v[78:81], v[180:183], v[220:223], v[78:81]
	v_mfma_f32_16x16x32_bf16 v[70:73], v[188:191], v[220:223], v[70:73]
	s_setprio 0
	s_barrier
; #define PG8_STAGE(bufoff, gbase, voff) do { _Pragma("unroll") for (int _i = 0; _i < 2; ++_i) \
;         __builtin_amdgcn_global_load_lds((const unsigned*)((const char*)(gbase) + (voff)[_i]), (LAS unsigned*)(lds + (bufoff) + ldsw + _i * 8192), 16, 0, 0); } while (0)
; #define PG8_LDA(dst, b, h) do { _Pragma("unroll") for (int m = 0; m < 4; ++m) _Pragma("unroll") for (int k = 0; k < 2; ++k) dst[m][k] = *(const LAS bf16x8*)(lds + PG8_SA(b, h) + aoff + m * 2048 + k * 1024); } while (0)
; #define PG8_LDB(dst, b, h) do { _Pragma("unroll") for (int n = 0; n < 2; ++n) _Pragma("unroll") for (int k = 0; k < 2; ++k) dst[n][k] = *(const LAS bf16x8*)(lds + PG8_SB(b, h) + boff + n * 2048 + k * 1024); } while (0)
; #define PG8_WAIT_V(n) asm volatile("s_waitcnt vmcnt(" #n ")" ::: "memory")
; #define PG8_BAR __builtin_amdgcn_s_barrier()
; template <class Epi, class Sched>
; __device__ __forceinline__ void gemm_phase(LAS unsigned char* lds, const Gemm g, const Sched S, const Epi E, const int tid) {
;     ...
;         for (int t = 0; t < nt; t += 2) {
;             const bool last = (t == nt - 2);
;             const char* a1 = cA + (size_t)(t + 1) * kstep;
;             const char* a2 = last ? nA : cA + (size_t)(t + 2) * kstep; const char* b2 = last ? nB : cB + (size_t)(t + 2) * kstep;
;             const char* a3 = a2 + kstep; const char* b3 = b2 + kstep;
;             PG8_LDB(B0, 0, 0); PG8_LDB(B1, 0, 1); PG8_SCHED; PG8_LDA(At, 0, 0); PG8_STAGE(PG8_SA(1, 1), a1 + hstepA, voffA);
;             PG8_WAIT_V(8); PG8_WAIT_L(0); PG8_BAR; PG8_MMA(0, 0, At, B0); PG8_MMA(0, 1, At, B1); PG8_BAR; PG8_SCHED;
;             PG8_LDA(At, 0, 1); PG8_STAGE(PG8_SB(0, 0), b2, voffB); PG8_STAGE(PG8_SB(0, 1), b2 + hstepB, voffB); PG8_STAGE(PG8_SA(0, 0), a2, voffA);
;             PG8_WAIT_V(8); PG8_WAIT_L(0); PG8_BAR; PG8_MMA(1, 0, At, B0); PG8_MMA(1, 1, At, B1); PG8_BAR; PG8_SCHED;
;             PG8_LDB(B0, 1, 0); PG8_LDB(B1, 1, 1); PG8_SCHED; PG8_LDA(At, 1, 0); PG8_STAGE(PG8_SA(0, 1), a2 + hstepA, voffA);
;             PG8_WAIT_V(8); PG8_WAIT_L(0); PG8_BAR; PG8_MMA(0, 0, At, B0); PG8_MMA(0, 1, At, B1); PG8_BAR; PG8_SCHED;
;             PG8_LDA(At, 1, 1); PG8_STAGE(PG8_SB(1, 0), b3, voffB); PG8_STAGE(PG8_SB(1, 1), b3 + hstepB, voffB); PG8_STAGE(PG8_SA(1, 0), a3, voffA);
;             PG8_WAIT_V(8); PG8_WAIT_L(0); PG8_BAR; PG8_MMA(1, 0, At, B0); PG8_MMA(1, 1, At, B1); PG8_BAR; PG8_SCHED;
;         }
	s_add_i32 s10, vcc_lo, s37
	v_lshl_add_u64 v[154:155], v[154:155], 0, s[64:65]
	s_mov_b32 m0, s10
	ds_read_b128 v[192:195], v158 offset:49152
	ds_read_b128 v[196:199], v158 offset:50176
	ds_read_b128 v[200:203], v158 offset:51200
	ds_read_b128 v[204:207], v158 offset:52224
	ds_read_b128 v[208:211], v158 offset:53248
	ds_read_b128 v[212:215], v158 offset:54272
	ds_read_b128 v[216:219], v158 offset:55296
	ds_read_b128 v[220:223], v158 offset:56320
	global_load_lds_dwordx4 v[154:155], off
	s_add_i32 m0, s10, 0x2000
	s_add_u32 s10, s46, 0x40080
	v_lshl_add_u64 v[154:155], v[224:225], 0, s[64:65]
	s_addc_u32 s11, s47, 0
	s_add_i32 s46, vcc_hi, s37
	global_load_lds_dwordx4 v[154:155], off
	v_lshl_add_u64 v[154:155], s[10:11], 0, v[140:141]
	s_mov_b32 m0, s46
	s_nop 0
	global_load_lds_dwordx4 v[154:155], off
	v_lshl_add_u64 v[154:155], s[10:11], 0, v[144:145]
	s_add_i32 m0, s46, 0x2000
	s_nop 0
	global_load_lds_dwordx4 v[154:155], off
	v_lshl_add_u64 v[154:155], v[226:227], 0, s[64:65]
	s_mov_b32 m0, s88
	s_nop 0
	global_load_lds_dwordx4 v[154:155], off
	v_lshl_add_u64 v[154:155], v[228:229], 0, s[64:65]
	s_mov_b32 m0, s89
	s_nop 0
	global_load_lds_dwordx4 v[154:155], off
	s_waitcnt vmcnt(8)
	s_waitcnt lgkmcnt(0)
	s_barrier
	s_setprio 1
	s_waitcnt lgkmcnt(0)
	v_mfma_f32_16x16x32_bf16 v[58:61], v[130:133], v[192:195], v[58:61]
	v_mfma_f32_16x16x32_bf16 v[50:53], v[150:153], v[192:195], v[50:53]
	v_mfma_f32_16x16x32_bf16 v[42:45], v[130:133], v[200:203], v[42:45]
	v_mfma_f32_16x16x32_bf16 v[34:37], v[150:153], v[200:203], v[34:37]
	v_mfma_f32_16x16x32_bf16 v[26:29], v[130:133], v[208:211], v[26:29]
	v_mfma_f32_16x16x32_bf16 v[18:21], v[150:153], v[208:211], v[18:21]
	v_mfma_f32_16x16x32_bf16 v[10:13], v[130:133], v[216:219], v[10:13]
	v_mfma_f32_16x16x32_bf16 v[6:9], v[150:153], v[216:219], v[6:9]
	v_mfma_f32_16x16x32_bf16 v[58:61], v[134:137], v[196:199], v[58:61]
	v_mfma_f32_16x16x32_bf16 v[50:53], v[160:163], v[196:199], v[50:53]
	v_mfma_f32_16x16x32_bf16 v[42:45], v[134:137], v[204:207], v[42:45]
	v_mfma_f32_16x16x32_bf16 v[34:37], v[160:163], v[204:207], v[34:37]
	v_mfma_f32_16x16x32_bf16 v[26:29], v[134:137], v[212:215], v[26:29]
	v_mfma_f32_16x16x32_bf16 v[18:21], v[160:163], v[212:215], v[18:21]
	v_mfma_f32_16x16x32_bf16 v[10:13], v[134:137], v[220:223], v[10:13]
	v_mfma_f32_16x16x32_bf16 v[6:9], v[160:163], v[220:223], v[6:9]
	v_mfma_f32_16x16x32_bf16 v[62:65], v[164:167], v[192:195], v[62:65]
	v_mfma_f32_16x16x32_bf16 v[54:57], v[184:187], v[192:195], v[54:57]
	v_mfma_f32_16x16x32_bf16 v[46:49], v[164:167], v[200:203], v[46:49]
	v_mfma_f32_16x16x32_bf16 v[38:41], v[184:187], v[200:203], v[38:41]
	v_mfma_f32_16x16x32_bf16 v[30:33], v[164:167], v[208:211], v[30:33]
	v_mfma_f32_16x16x32_bf16 v[22:25], v[184:187], v[208:211], v[22:25]
	v_mfma_f32_16x16x32_bf16 v[14:17], v[164:167], v[216:219], v[14:17]
	v_mfma_f32_16x16x32_bf16 v[2:5], v[184:187], v[216:219], v[2:5]
	v_mfma_f32_16x16x32_bf16 v[62:65], v[180:183], v[196:199], v[62:65]
	v_mfma_f32_16x16x32_bf16 v[54:57], v[188:191], v[196:199], v[54:57]
	v_mfma_f32_16x16x32_bf16 v[46:49], v[180:183], v[204:207], v[46:49]
	v_mfma_f32_16x16x32_bf16 v[38:41], v[188:191], v[204:207], v[38:41]
	v_mfma_f32_16x16x32_bf16 v[30:33], v[180:183], v[212:215], v[30:33]
	v_mfma_f32_16x16x32_bf16 v[22:25], v[188:191], v[212:215], v[22:25]
	v_mfma_f32_16x16x32_bf16 v[14:17], v[180:183], v[220:223], v[14:17]
	v_mfma_f32_16x16x32_bf16 v[2:5], v[188:191], v[220:223], v[2:5]
	s_setprio 0
	s_barrier
	s_add_i32 s97, s97, 2
	s_add_u32 s95, s95, 0x100
	s_addc_u32 s96, s96, 0
	s_add_u32 s44, s44, 0x100
	s_addc_u32 s45, s45, 0
	s_cmp_gt_u32 s97, 13
	s_cbranch_scc0 .LBB0_332
	s_and_b64 vcc, exec, s[14:15]
	s_cbranch_vccz .LBB0_335
	s_barrier

; #define PG8_STAGE(bufoff, gbase, voff) do { _Pragma("unroll") for (int _i = 0; _i < 2; ++_i) \
;         __builtin_amdgcn_global_load_lds((const unsigned*)((const char*)(gbase) + (voff)[_i]), (LAS unsigned*)(lds + (bufoff) + ldsw + _i * 8192), 16, 0, 0); } while (0)
; #define PG8_LDA(dst, b, h) do { _Pragma("unroll") for (int m = 0; m < 4; ++m) _Pragma("unroll") for (int k = 0; k < 2; ++k) dst[m][k] = *(const LAS bf16x8*)(lds + PG8_SA(b, h) + aoff + m * 2048 + k * 1024); } while (0)
; #define PG8_LDB(dst, b, h) do { _Pragma("unroll") for (int n = 0; n < 2; ++n) _Pragma("unroll") for (int k = 0; k < 2; ++k) dst[n][k] = *(const LAS bf16x8*)(lds + PG8_SB(b, h) + boff + n * 2048 + k * 1024); } while (0)
; #define PG8_MMA(ai, bj, At, Bt) do { __builtin_amdgcn_s_setprio(1); _Pragma("unroll") for (int m = 0; m < 4; ++m) _Pragma("unroll") for (int n = 0; n < 2; ++n) _Pragma("unroll") for (int k = 0; k < 2; ++k) \
;         acc[ai][bj][m][n] = __builtin_amdgcn_mfma_f32_16x16x32_bf16(Bt[n][k], At[m][k], acc[ai][bj][m][n], 0, 0, 0); __builtin_amdgcn_s_setprio(0); } while (0)
; #define PG8_WAIT_V(n) asm volatile("s_waitcnt vmcnt(" #n ")" ::: "memory")
; #define PG8_WAIT_L(n) asm volatile("s_waitcnt lgkmcnt(" #n ")" ::: "memory")
; #define PG8_BAR __builtin_amdgcn_s_barrier()
; #define PG8_SCHED __builtin_amdgcn_sched_barrier(0)
; template <class Epi, class Sched>
; __device__ __forceinline__ void gemm_phase(LAS unsigned char* lds, const Gemm g, const Sched S, const Epi E, const int tid) {
;     ...
;             PG8_LDB(B0, 0, 0); PG8_LDB(B1, 0, 1); PG8_SCHED; PG8_LDA(At, 0, 0); PG8_STAGE(PG8_SA(1, 1), a1 + hstepA, voffA);
;             PG8_WAIT_V(8); PG8_WAIT_L(0); PG8_BAR; PG8_MMA(0, 0, At, B0); PG8_MMA(0, 1, At, B1); PG8_BAR; PG8_SCHED;
;             PG8_LDA(At, 0, 1); PG8_STAGE(PG8_SB(0, 0), b2, voffB); PG8_STAGE(PG8_SB(0, 1), b2 + hstepB, voffB); PG8_STAGE(PG8_SA(0, 0), a2, voffA);
;             PG8_WAIT_V(8); PG8_WAIT_L(0); PG8_BAR; PG8_MMA(1, 0, At, B0); PG8_MMA(1, 1, At, B1); PG8_BAR; PG8_SCHED;
.LBB0_471:
	s_add_u32 s12, s10, 0xfffc0080
	s_addc_u32 s13, s11, -1
	s_add_i32 s83, 0, 0x10000
	s_cmp_eq_u32 s82, 12
	s_cselect_b32 s15, s9, s13
	s_cselect_b32 s14, s45, s12
	s_cselect_b32 s13, s43, s62
	s_cselect_b32 s12, s48, s49
	s_add_i32 vcc_lo, 0, 0x14000
	v_add_u32_e32 v154, s83, v165
	v_add_u32_e32 v162, vcc_lo, v165
	ds_read_b128 v[50:53], v154
	ds_read_b128 v[102:105], v154 offset:1024
	ds_read_b128 v[150:153], v154 offset:2048
	ds_read_b128 v[154:157], v154 offset:3072
	ds_read_b128 v[158:161], v162
	ds_read_b128 v[180:183], v162 offset:1024
	ds_read_b128 v[184:187], v162 offset:2048
	ds_read_b128 v[188:191], v162 offset:3072
	v_lshl_add_u64 v[162:163], s[10:11], 0, v[148:149]
	s_add_i32 m0, s41, 0xc000
	ds_read_b128 v[192:195], v166
	ds_read_b128 v[196:199], v166 offset:1024
	ds_read_b128 v[200:203], v166 offset:2048
	ds_read_b128 v[204:207], v166 offset:3072
	ds_read_b128 v[208:211], v166 offset:4096
	ds_read_b128 v[212:215], v166 offset:5120
	ds_read_b128 v[216:219], v166 offset:6144
	ds_read_b128 v[220:223], v166 offset:7168
	global_load_lds_dwordx4 v[162:163], off
	v_lshl_add_u64 v[162:163], s[10:11], 0, v[146:147]
	s_add_i32 m0, s41, 0xe000
	s_nop 0
	global_load_lds_dwordx4 v[162:163], off
	s_waitcnt vmcnt(8)
	s_waitcnt lgkmcnt(0)
	s_barrier
	s_setprio 1
	s_waitcnt lgkmcnt(0)
	v_mfma_f32_16x16x32_bf16 v[130:133], v[50:53], v[192:195], v[130:133]
	v_mfma_f32_16x16x32_bf16 v[126:129], v[150:153], v[192:195], v[126:129]
	v_mfma_f32_16x16x32_bf16 v[114:117], v[50:53], v[200:203], v[114:117]
	v_mfma_f32_16x16x32_bf16 v[110:113], v[150:153], v[200:203], v[110:113]
	v_mfma_f32_16x16x32_bf16 v[94:97], v[50:53], v[208:211], v[94:97]
	v_mfma_f32_16x16x32_bf16 v[90:93], v[150:153], v[208:211], v[90:93]
	v_mfma_f32_16x16x32_bf16 v[78:81], v[50:53], v[216:219], v[78:81]
	v_mfma_f32_16x16x32_bf16 v[74:77], v[150:153], v[216:219], v[74:77]
	v_mfma_f32_16x16x32_bf16 v[130:133], v[102:105], v[196:199], v[130:133]
	v_mfma_f32_16x16x32_bf16 v[126:129], v[154:157], v[196:199], v[126:129]
	v_mfma_f32_16x16x32_bf16 v[114:117], v[102:105], v[204:207], v[114:117]
	v_mfma_f32_16x16x32_bf16 v[110:113], v[154:157], v[204:207], v[110:113]
	v_mfma_f32_16x16x32_bf16 v[94:97], v[102:105], v[212:215], v[94:97]
	v_mfma_f32_16x16x32_bf16 v[90:93], v[154:157], v[212:215], v[90:93]
	v_mfma_f32_16x16x32_bf16 v[78:81], v[102:105], v[220:223], v[78:81]
	v_mfma_f32_16x16x32_bf16 v[74:77], v[154:157], v[220:223], v[74:77]
	v_mfma_f32_16x16x32_bf16 v[134:137], v[158:161], v[192:195], v[134:137]
	v_mfma_f32_16x16x32_bf16 v[122:125], v[184:187], v[192:195], v[122:125]
	v_mfma_f32_16x16x32_bf16 v[118:121], v[158:161], v[200:203], v[118:121]
	v_mfma_f32_16x16x32_bf16 v[106:109], v[184:187], v[200:203], v[106:109]
	v_mfma_f32_16x16x32_bf16 v[98:101], v[158:161], v[208:211], v[98:101]
	v_mfma_f32_16x16x32_bf16 v[86:89], v[184:187], v[208:211], v[86:89]
	v_mfma_f32_16x16x32_bf16 v[82:85], v[158:161], v[216:219], v[82:85]
	v_mfma_f32_16x16x32_bf16 v[70:73], v[184:187], v[216:219], v[70:73]
	v_mfma_f32_16x16x32_bf16 v[134:137], v[180:183], v[196:199], v[134:137]
	v_mfma_f32_16x16x32_bf16 v[122:125], v[188:191], v[196:199], v[122:125]
	v_mfma_f32_16x16x32_bf16 v[118:121], v[180:183], v[204:207], v[118:121]
	v_mfma_f32_16x16x32_bf16 v[106:109], v[188:191], v[204:207], v[106:109]
	v_mfma_f32_16x16x32_bf16 v[98:101], v[180:183], v[212:215], v[98:101]
	v_mfma_f32_16x16x32_bf16 v[86:89], v[188:191], v[212:215], v[86:89]
	v_mfma_f32_16x16x32_bf16 v[82:85], v[180:183], v[220:223], v[82:85]
	v_mfma_f32_16x16x32_bf16 v[70:73], v[188:191], v[220:223], v[70:73]
	s_setprio 0
	s_barrier
	s_add_i32 s83, s83, s37
	v_lshl_add_u64 v[162:163], s[12:13], 0, v[140:141]
	s_mov_b32 m0, s83
	ds_read_b128 v[192:195], v166 offset:16384
	ds_read_b128 v[196:199], v166 offset:17408
	ds_read_b128 v[200:203], v166 offset:18432
	ds_read_b128 v[204:207], v166 offset:19456
	ds_read_b128 v[208:211], v166 offset:20480
	ds_read_b128 v[212:215], v166 offset:21504
	ds_read_b128 v[216:219], v166 offset:22528
	ds_read_b128 v[220:223], v166 offset:23552
	global_load_lds_dwordx4 v[162:163], off
	s_add_i32 m0, s83, 0x2000
	s_add_u32 s84, s12, 0x40000
	v_lshl_add_u64 v[224:225], s[12:13], 0, v[144:145]
	s_addc_u32 s85, s13, 0
	s_add_i32 s83, vcc_lo, s37
	global_load_lds_dwordx4 v[224:225], off
	v_lshl_add_u64 v[226:227], s[84:85], 0, v[140:141]
	s_mov_b32 m0, s83
	v_lshl_add_u64 v[228:229], s[14:15], 0, v[142:143]
	global_load_lds_dwordx4 v[226:227], off
	v_lshl_add_u64 v[226:227], s[84:85], 0, v[144:145]
	s_add_i32 m0, s83, 0x2000
	s_nop 0
	global_load_lds_dwordx4 v[226:227], off
	v_lshl_add_u64 v[226:227], s[14:15], 0, v[138:139]
	s_mov_b32 m0, s41
	s_nop 0
	global_load_lds_dwordx4 v[226:227], off
	s_mov_b32 m0, s90
	s_nop 0
	global_load_lds_dwordx4 v[228:229], off
	s_waitcnt vmcnt(8)
	s_waitcnt lgkmcnt(0)
	s_barrier
; #define PG8_STAGE(bufoff, gbase, voff) do { _Pragma("unroll") for (int _i = 0; _i < 2; ++_i) \
;         __builtin_amdgcn_global_load_lds((const unsigned*)((const char*)(gbase) + (voff)[_i]), (LAS unsigned*)(lds + (bufoff) + ldsw + _i * 8192), 16, 0, 0); } while (0)
; #define PG8_LDA(dst, b, h) do { _Pragma("unroll") for (int m = 0; m < 4; ++m) _Pragma("unroll") for (int k = 0; k < 2; ++k) dst[m][k] = *(const LAS bf16x8*)(lds + PG8_SA(b, h) + aoff + m * 2048 + k * 1024); } while (0)
; #define PG8_LDB(dst, b, h) do { _Pragma("unroll") for (int n = 0; n < 2; ++n) _Pragma("unroll") for (int k = 0; k < 2; ++k) dst[n][k] = *(const LAS bf16x8*)(lds + PG8_SB(b, h) + boff + n * 2048 + k * 1024); } while (0)
; #define PG8_MMA(ai, bj, At, Bt) do { __builtin_amdgcn_s_setprio(1); _Pragma("unroll") for (int m = 0; m < 4; ++m) _Pragma("unroll") for (int n = 0; n < 2; ++n) _Pragma("unroll") for (int k = 0; k < 2; ++k) \
;         acc[ai][bj][m][n] = __builtin_amdgcn_mfma_f32_16x16x32_bf16(Bt[n][k], At[m][k], acc[ai][bj][m][n], 0, 0, 0); __builtin_amdgcn_s_setprio(0); } while (0)
; #define PG8_WAIT_V(n) asm volatile("s_waitcnt vmcnt(" #n ")" ::: "memory")
; #define PG8_WAIT_L(n) asm volatile("s_waitcnt lgkmcnt(" #n ")" ::: "memory")
; #define PG8_BAR __builtin_amdgcn_s_barrier()
; #define PG8_SCHED __builtin_amdgcn_sched_barrier(0)
; template <class Epi, class Sched>
; __device__ __forceinline__ void gemm_phase(LAS unsigned char* lds, const Gemm g, const Sched S, const Epi E, const int tid) {
;     ...
;             PG8_WAIT_V(8); PG8_WAIT_L(0); PG8_BAR; PG8_MMA(1, 0, At, B0); PG8_MMA(1, 1, At, B1); PG8_BAR; PG8_SCHED;
;             PG8_LDB(B0, 1, 0); PG8_LDB(B1, 1, 1); PG8_SCHED; PG8_LDA(At, 1, 0); PG8_STAGE(PG8_SA(0, 1), a2 + hstepA, voffA);
;             PG8_WAIT_V(8); PG8_WAIT_L(0); PG8_BAR; PG8_MMA(0, 0, At, B0); PG8_MMA(0, 1, At, B1); PG8_BAR; PG8_SCHED;
	s_setprio 1
	s_waitcnt lgkmcnt(0)
	v_mfma_f32_16x16x32_bf16 v[62:65], v[50:53], v[192:195], v[62:65]
	v_mfma_f32_16x16x32_bf16 v[58:61], v[150:153], v[192:195], v[58:61]
	v_mfma_f32_16x16x32_bf16 v[42:45], v[50:53], v[200:203], v[42:45]
	v_mfma_f32_16x16x32_bf16 v[38:41], v[150:153], v[200:203], v[38:41]
	v_mfma_f32_16x16x32_bf16 v[26:29], v[50:53], v[208:211], v[26:29]
	v_mfma_f32_16x16x32_bf16 v[22:25], v[150:153], v[208:211], v[22:25]
	v_mfma_f32_16x16x32_bf16 v[10:13], v[50:53], v[216:219], v[10:13]
	v_mfma_f32_16x16x32_bf16 v[6:9], v[150:153], v[216:219], v[6:9]
	v_mfma_f32_16x16x32_bf16 v[62:65], v[102:105], v[196:199], v[62:65]
	v_mfma_f32_16x16x32_bf16 v[58:61], v[154:157], v[196:199], v[58:61]
	v_mfma_f32_16x16x32_bf16 v[42:45], v[102:105], v[204:207], v[42:45]
	v_mfma_f32_16x16x32_bf16 v[38:41], v[154:157], v[204:207], v[38:41]
	v_mfma_f32_16x16x32_bf16 v[26:29], v[102:105], v[212:215], v[26:29]
	v_mfma_f32_16x16x32_bf16 v[22:25], v[154:157], v[212:215], v[22:25]
	v_mfma_f32_16x16x32_bf16 v[10:13], v[102:105], v[220:223], v[10:13]
	v_mfma_f32_16x16x32_bf16 v[6:9], v[154:157], v[220:223], v[6:9]
	v_mfma_f32_16x16x32_bf16 v[54:57], v[184:187], v[192:195], v[54:57]
	v_mfma_f32_16x16x32_bf16 v[46:49], v[158:161], v[200:203], v[46:49]
	v_mfma_f32_16x16x32_bf16 v[34:37], v[184:187], v[200:203], v[34:37]
	v_mfma_f32_16x16x32_bf16 v[30:33], v[158:161], v[208:211], v[30:33]
	v_mfma_f32_16x16x32_bf16 v[18:21], v[184:187], v[208:211], v[18:21]
	v_mfma_f32_16x16x32_bf16 v[14:17], v[158:161], v[216:219], v[14:17]
	v_mfma_f32_16x16x32_bf16 v[2:5], v[184:187], v[216:219], v[2:5]
	v_mfma_f32_16x16x32_bf16 v[50:53], v[158:161], v[192:195], v[66:69]
	v_mfma_f32_16x16x32_bf16 v[54:57], v[188:191], v[196:199], v[54:57]
	v_mfma_f32_16x16x32_bf16 v[46:49], v[180:183], v[204:207], v[46:49]
	v_mfma_f32_16x16x32_bf16 v[34:37], v[188:191], v[204:207], v[34:37]
	v_mfma_f32_16x16x32_bf16 v[30:33], v[180:183], v[212:215], v[30:33]
	v_mfma_f32_16x16x32_bf16 v[18:21], v[188:191], v[212:215], v[18:21]
	v_mfma_f32_16x16x32_bf16 v[14:17], v[180:183], v[220:223], v[14:17]
	v_mfma_f32_16x16x32_bf16 v[2:5], v[188:191], v[220:223], v[2:5]
	v_mfma_f32_16x16x32_bf16 v[50:53], v[180:183], v[196:199], v[50:53]
	s_setprio 0
	s_barrier
	s_add_i32 s83, 0, 0x18000
	s_add_i32 s84, 0, 0x1c000
	v_add_u32_e32 v154, s83, v165
	v_add_u32_e32 v167, s84, v165
	ds_read_b128 v[66:69], v154
	ds_read_b128 v[102:105], v154 offset:1024
	ds_read_b128 v[150:153], v154 offset:2048
	ds_read_b128 v[154:157], v154 offset:3072
	ds_read_b128 v[158:161], v167
	ds_read_b128 v[180:183], v167 offset:1024
	ds_read_b128 v[184:187], v167 offset:2048
	ds_read_b128 v[188:191], v167 offset:3072
	s_add_u32 s14, s14, 0x40000
	s_addc_u32 s15, s15, 0
	s_mov_b32 m0, s91
	v_lshl_add_u64 v[230:231], s[14:15], 0, v[138:139]
	ds_read_b128 v[192:195], v166 offset:32768
	ds_read_b128 v[196:199], v166 offset:33792
	ds_read_b128 v[200:203], v166 offset:34816
	ds_read_b128 v[204:207], v166 offset:35840
	ds_read_b128 v[208:211], v166 offset:36864
	ds_read_b128 v[212:215], v166 offset:37888
	ds_read_b128 v[216:219], v166 offset:38912
	ds_read_b128 v[220:223], v166 offset:39936
	global_load_lds_dwordx4 v[230:231], off
	v_lshl_add_u64 v[230:231], s[14:15], 0, v[142:143]
	s_mov_b32 m0, s68
	s_nop 0
	global_load_lds_dwordx4 v[230:231], off
	s_waitcnt vmcnt(8)
	s_waitcnt lgkmcnt(0)
	s_barrier
	s_setprio 1
	s_waitcnt lgkmcnt(0)
	v_mfma_f32_16x16x32_bf16 v[130:133], v[66:69], v[192:195], v[130:133]
	v_mfma_f32_16x16x32_bf16 v[126:129], v[150:153], v[192:195], v[126:129]
	v_mfma_f32_16x16x32_bf16 v[114:117], v[66:69], v[200:203], v[114:117]
	v_mfma_f32_16x16x32_bf16 v[110:113], v[150:153], v[200:203], v[110:113]
	v_mfma_f32_16x16x32_bf16 v[94:97], v[66:69], v[208:211], v[94:97]
	v_mfma_f32_16x16x32_bf16 v[90:93], v[150:153], v[208:211], v[90:93]
	v_mfma_f32_16x16x32_bf16 v[78:81], v[66:69], v[216:219], v[78:81]
	v_mfma_f32_16x16x32_bf16 v[74:77], v[150:153], v[216:219], v[74:77]
	v_mfma_f32_16x16x32_bf16 v[130:133], v[102:105], v[196:199], v[130:133]
	v_mfma_f32_16x16x32_bf16 v[126:129], v[154:157], v[196:199], v[126:129]
	v_mfma_f32_16x16x32_bf16 v[114:117], v[102:105], v[204:207], v[114:117]
	v_mfma_f32_16x16x32_bf16 v[110:113], v[154:157], v[204:207], v[110:113]
	v_mfma_f32_16x16x32_bf16 v[94:97], v[102:105], v[212:215], v[94:97]
	v_mfma_f32_16x16x32_bf16 v[90:93], v[154:157], v[212:215], v[90:93]
	v_mfma_f32_16x16x32_bf16 v[78:81], v[102:105], v[220:223], v[78:81]
	v_mfma_f32_16x16x32_bf16 v[74:77], v[154:157], v[220:223], v[74:77]
	v_mfma_f32_16x16x32_bf16 v[134:137], v[158:161], v[192:195], v[134:137]
	v_mfma_f32_16x16x32_bf16 v[122:125], v[184:187], v[192:195], v[122:125]
	v_mfma_f32_16x16x32_bf16 v[118:121], v[158:161], v[200:203], v[118:121]
	v_mfma_f32_16x16x32_bf16 v[106:109], v[184:187], v[200:203], v[106:109]
	v_mfma_f32_16x16x32_bf16 v[98:101], v[158:161], v[208:211], v[98:101]
	v_mfma_f32_16x16x32_bf16 v[86:89], v[184:187], v[208:211], v[86:89]
	v_mfma_f32_16x16x32_bf16 v[82:85], v[158:161], v[216:219], v[82:85]
	v_mfma_f32_16x16x32_bf16 v[70:73], v[184:187], v[216:219], v[70:73]
	v_mfma_f32_16x16x32_bf16 v[134:137], v[180:183], v[196:199], v[134:137]
	v_mfma_f32_16x16x32_bf16 v[122:125], v[188:191], v[196:199], v[122:125]
	v_mfma_f32_16x16x32_bf16 v[118:121], v[180:183], v[204:207], v[118:121]
	v_mfma_f32_16x16x32_bf16 v[106:109], v[188:191], v[204:207], v[106:109]
	v_mfma_f32_16x16x32_bf16 v[98:101], v[180:183], v[212:215], v[98:101]
	v_mfma_f32_16x16x32_bf16 v[86:89], v[188:191], v[212:215], v[86:89]
	v_mfma_f32_16x16x32_bf16 v[82:85], v[180:183], v[220:223], v[82:85]
	v_mfma_f32_16x16x32_bf16 v[70:73], v[188:191], v[220:223], v[70:73]
	s_setprio 0
	s_barrier
; #define PG8_STAGE(bufoff, gbase, voff) do { _Pragma("unroll") for (int _i = 0; _i < 2; ++_i) \
;         __builtin_amdgcn_global_load_lds((const unsigned*)((const char*)(gbase) + (voff)[_i]), (LAS unsigned*)(lds + (bufoff) + ldsw + _i * 8192), 16, 0, 0); } while (0)
; #define PG8_LDA(dst, b, h) do { _Pragma("unroll") for (int m = 0; m < 4; ++m) _Pragma("unroll") for (int k = 0; k < 2; ++k) dst[m][k] = *(const LAS bf16x8*)(lds + PG8_SA(b, h) + aoff + m * 2048 + k * 1024); } while (0)
; #define PG8_MMA(ai, bj, At, Bt) do { __builtin_amdgcn_s_setprio(1); _Pragma("unroll") for (int m = 0; m < 4; ++m) _Pragma("unroll") for (int n = 0; n < 2; ++n) _Pragma("unroll") for (int k = 0; k < 2; ++k) \
;         acc[ai][bj][m][n] = __builtin_amdgcn_mfma_f32_16x16x32_bf16(Bt[n][k], At[m][k], acc[ai][bj][m][n], 0, 0, 0); __builtin_amdgcn_s_setprio(0); } while (0)
; #define PG8_WAIT_V(n) asm volatile("s_waitcnt vmcnt(" #n ")" ::: "memory")
; #define PG8_WAIT_L(n) asm volatile("s_waitcnt lgkmcnt(" #n ")" ::: "memory")
; #define PG8_BAR __builtin_amdgcn_s_barrier()
; #define PG8_SCHED __builtin_amdgcn_sched_barrier(0)
; template <class Epi, class Sched>
; __device__ __forceinline__ void gemm_phase(LAS unsigned char* lds, const Gemm g, const Sched S, const Epi E, const int tid) {
;     ...
;             PG8_LDA(At, 1, 1); PG8_STAGE(PG8_SB(1, 0), b3, voffB); PG8_STAGE(PG8_SB(1, 1), b3 + hstepB, voffB); PG8_STAGE(PG8_SA(1, 0), a3, voffA);
;             PG8_WAIT_V(8); PG8_WAIT_L(0); PG8_BAR; PG8_MMA(1, 0, At, B0); PG8_MMA(1, 1, At, B1); PG8_BAR; PG8_SCHED;
;         }
	s_add_i32 s14, s83, s37
	v_lshl_add_u64 v[162:163], v[162:163], 0, s[64:65]
	s_mov_b32 m0, s14
	ds_read_b128 v[192:195], v166 offset:49152
	ds_read_b128 v[196:199], v166 offset:50176
	ds_read_b128 v[200:203], v166 offset:51200
	ds_read_b128 v[204:207], v166 offset:52224
	ds_read_b128 v[208:211], v166 offset:53248
	ds_read_b128 v[212:215], v166 offset:54272
	ds_read_b128 v[216:219], v166 offset:55296
	ds_read_b128 v[220:223], v166 offset:56320
	global_load_lds_dwordx4 v[162:163], off
	s_add_i32 m0, s14, 0x2000
	s_add_u32 s12, s12, 0x40080
	v_lshl_add_u64 v[162:163], v[224:225], 0, s[64:65]
	s_addc_u32 s13, s13, 0
	s_add_i32 s14, s84, s37
	global_load_lds_dwordx4 v[162:163], off
	v_lshl_add_u64 v[162:163], s[12:13], 0, v[140:141]
	s_mov_b32 m0, s14
	s_nop 0
	global_load_lds_dwordx4 v[162:163], off
	v_lshl_add_u64 v[162:163], s[12:13], 0, v[144:145]
	s_add_i32 m0, s14, 0x2000
	s_nop 0
	global_load_lds_dwordx4 v[162:163], off
	v_lshl_add_u64 v[162:163], v[226:227], 0, s[64:65]
	s_mov_b32 m0, s29
	s_nop 0
	global_load_lds_dwordx4 v[162:163], off
	v_lshl_add_u64 v[162:163], v[228:229], 0, s[64:65]
	s_mov_b32 m0, s92
	s_nop 0
	global_load_lds_dwordx4 v[162:163], off
	s_waitcnt vmcnt(8)
	s_waitcnt lgkmcnt(0)
	s_barrier
	s_setprio 1
	s_waitcnt lgkmcnt(0)
	v_mfma_f32_16x16x32_bf16 v[62:65], v[66:69], v[192:195], v[62:65]
	v_mfma_f32_16x16x32_bf16 v[58:61], v[150:153], v[192:195], v[58:61]
	v_mfma_f32_16x16x32_bf16 v[42:45], v[66:69], v[200:203], v[42:45]
	v_mfma_f32_16x16x32_bf16 v[38:41], v[150:153], v[200:203], v[38:41]
	v_mfma_f32_16x16x32_bf16 v[26:29], v[66:69], v[208:211], v[26:29]
	v_mfma_f32_16x16x32_bf16 v[22:25], v[150:153], v[208:211], v[22:25]
	v_mfma_f32_16x16x32_bf16 v[10:13], v[66:69], v[216:219], v[10:13]
	v_mfma_f32_16x16x32_bf16 v[6:9], v[150:153], v[216:219], v[6:9]
	v_mfma_f32_16x16x32_bf16 v[62:65], v[102:105], v[196:199], v[62:65]
	v_mfma_f32_16x16x32_bf16 v[58:61], v[154:157], v[196:199], v[58:61]
	v_mfma_f32_16x16x32_bf16 v[42:45], v[102:105], v[204:207], v[42:45]
	v_mfma_f32_16x16x32_bf16 v[38:41], v[154:157], v[204:207], v[38:41]
	v_mfma_f32_16x16x32_bf16 v[26:29], v[102:105], v[212:215], v[26:29]
	v_mfma_f32_16x16x32_bf16 v[22:25], v[154:157], v[212:215], v[22:25]
	v_mfma_f32_16x16x32_bf16 v[10:13], v[102:105], v[220:223], v[10:13]
	v_mfma_f32_16x16x32_bf16 v[6:9], v[154:157], v[220:223], v[6:9]
	v_mfma_f32_16x16x32_bf16 v[50:53], v[158:161], v[192:195], v[50:53]
	v_mfma_f32_16x16x32_bf16 v[66:69], v[180:183], v[196:199], v[50:53]
	v_mfma_f32_16x16x32_bf16 v[50:53], v[184:187], v[192:195], v[54:57]
	v_mfma_f32_16x16x32_bf16 v[46:49], v[158:161], v[200:203], v[46:49]
	v_mfma_f32_16x16x32_bf16 v[34:37], v[184:187], v[200:203], v[34:37]
	v_mfma_f32_16x16x32_bf16 v[30:33], v[158:161], v[208:211], v[30:33]
	v_mfma_f32_16x16x32_bf16 v[18:21], v[184:187], v[208:211], v[18:21]
	v_mfma_f32_16x16x32_bf16 v[14:17], v[158:161], v[216:219], v[14:17]
	v_mfma_f32_16x16x32_bf16 v[2:5], v[184:187], v[216:219], v[2:5]
	v_mfma_f32_16x16x32_bf16 v[54:57], v[188:191], v[196:199], v[50:53]
	v_mfma_f32_16x16x32_bf16 v[46:49], v[180:183], v[204:207], v[46:49]
	v_mfma_f32_16x16x32_bf16 v[34:37], v[188:191], v[204:207], v[34:37]
	v_mfma_f32_16x16x32_bf16 v[30:33], v[180:183], v[212:215], v[30:33]
	v_mfma_f32_16x16x32_bf16 v[18:21], v[188:191], v[212:215], v[18:21]
	v_mfma_f32_16x16x32_bf16 v[14:17], v[180:183], v[220:223], v[14:17]
	v_mfma_f32_16x16x32_bf16 v[2:5], v[188:191], v[220:223], v[2:5]
	s_setprio 0
	s_barrier
	s_add_i32 s82, s82, 2
	s_add_u32 s49, s49, 0x100
	s_addc_u32 s62, s62, 0
	s_add_u32 s10, s10, 0x100
	s_addc_u32 s11, s11, 0
	s_cmp_gt_u32 s82, 13
	s_cbranch_scc0 .LBB0_471
	s_and_b64 vcc, exec, s[18:19]
	s_cbranch_vccz .LBB0_474
	s_barrier

; #define PG8_STAGE(bufoff, gbase, voff) do { _Pragma("unroll") for (int _i = 0; _i < 2; ++_i) \
;         __builtin_amdgcn_global_load_lds((const unsigned*)((const char*)(gbase) + (voff)[_i]), (LAS unsigned*)(lds + (bufoff) + ldsw + _i * 8192), 16, 0, 0); } while (0)
; #define PG8_LDA(dst, b, h) do { _Pragma("unroll") for (int m = 0; m < 4; ++m) _Pragma("unroll") for (int k = 0; k < 2; ++k) dst[m][k] = *(const LAS bf16x8*)(lds + PG8_SA(b, h) + aoff + m * 2048 + k * 1024); } while (0)
; #define PG8_LDB(dst, b, h) do { _Pragma("unroll") for (int n = 0; n < 2; ++n) _Pragma("unroll") for (int k = 0; k < 2; ++k) dst[n][k] = *(const LAS bf16x8*)(lds + PG8_SB(b, h) + boff + n * 2048 + k * 1024); } while (0)
; #define PG8_MMA(ai, bj, At, Bt) do { __builtin_amdgcn_s_setprio(1); _Pragma("unroll") for (int m = 0; m < 4; ++m) _Pragma("unroll") for (int n = 0; n < 2; ++n) _Pragma("unroll") for (int k = 0; k < 2; ++k) \
;         acc[ai][bj][m][n] = __builtin_amdgcn_mfma_f32_16x16x32_bf16(Bt[n][k], At[m][k], acc[ai][bj][m][n], 0, 0, 0); __builtin_amdgcn_s_setprio(0); } while (0)
; #define PG8_WAIT_V(n) asm volatile("s_waitcnt vmcnt(" #n ")" ::: "memory")
; #define PG8_WAIT_L(n) asm volatile("s_waitcnt lgkmcnt(" #n ")" ::: "memory")
; #define PG8_BAR __builtin_amdgcn_s_barrier()
; #define PG8_SCHED __builtin_amdgcn_sched_barrier(0)
; template <class Epi, class Sched>
; __device__ __forceinline__ void gemm_phase(LAS unsigned char* lds, const Gemm g, const Sched S, const Epi E, const int tid) {
;     ...
;             PG8_LDB(B0, 0, 0); PG8_LDB(B1, 0, 1); PG8_SCHED; PG8_LDA(At, 0, 0); PG8_STAGE(PG8_SA(1, 1), a1 + hstepA, voffA);
;             PG8_WAIT_V(8); PG8_WAIT_L(0); PG8_BAR; PG8_MMA(0, 0, At, B0); PG8_MMA(0, 1, At, B1); PG8_BAR; PG8_SCHED;
;             PG8_LDA(At, 0, 1); PG8_STAGE(PG8_SB(0, 0), b2, voffB); PG8_STAGE(PG8_SB(0, 1), b2 + hstepB, voffB); PG8_STAGE(PG8_SA(0, 0), a2, voffA);
;             PG8_WAIT_V(8); PG8_WAIT_L(0); PG8_BAR; PG8_MMA(1, 0, At, B0); PG8_MMA(1, 1, At, B1); PG8_BAR; PG8_SCHED;
.LBB0_778:
	s_add_i32 s94, s20, 2
	s_add_u32 s95, s18, 0x80
	s_addc_u32 s21, s19, 0
	s_add_i32 vcc_lo, 0, 0x10000
	s_cmp_eq_u32 s69, s20
	s_cselect_b32 s21, s9, s21
	s_cselect_b32 s20, s8, s95
	s_cselect_b32 s97, s17, s93
	s_cselect_b32 s96, s16, s92
	s_add_i32 s95, 0, 0x14000
	v_add_u32_e32 v142, vcc_lo, v198
	v_add_u32_e32 v167, s95, v198
	ds_read_b128 v[126:129], v142
	ds_read_b128 v[134:137], v142 offset:1024
	ds_read_b128 v[138:141], v142 offset:2048
	ds_read_b128 v[142:145], v142 offset:3072
	ds_read_b128 v[146:149], v167
	ds_read_b128 v[150:153], v167 offset:1024
	ds_read_b128 v[154:157], v167 offset:2048
	ds_read_b128 v[186:189], v167 offset:3072
	v_lshl_add_u64 v[224:225], s[18:19], 0, v[184:185]
	s_add_i32 m0, s37, 0xc000
	ds_read_b128 v[190:193], v199
	ds_read_b128 v[194:197], v199 offset:1024
	ds_read_b128 v[200:203], v199 offset:2048
	ds_read_b128 v[204:207], v199 offset:3072
	ds_read_b128 v[208:211], v199 offset:4096
	ds_read_b128 v[212:215], v199 offset:5120
	ds_read_b128 v[216:219], v199 offset:6144
	ds_read_b128 v[220:223], v199 offset:7168
	global_load_lds_dwordx4 v[224:225], off
	v_lshl_add_u64 v[224:225], s[18:19], 0, v[182:183]
	s_add_i32 m0, s37, 0xe000
	s_nop 0
	global_load_lds_dwordx4 v[224:225], off
	s_waitcnt vmcnt(8)
	s_waitcnt lgkmcnt(0)
	s_barrier
	s_setprio 1
	s_waitcnt lgkmcnt(0)
	v_mfma_f32_16x16x32_bf16 v[130:133], v[126:129], v[190:193], v[130:133]
	v_mfma_f32_16x16x32_bf16 v[122:125], v[138:141], v[190:193], v[122:125]
	v_mfma_f32_16x16x32_bf16 v[110:113], v[126:129], v[200:203], v[110:113]
	v_mfma_f32_16x16x32_bf16 v[106:109], v[138:141], v[200:203], v[106:109]
	v_mfma_f32_16x16x32_bf16 v[94:97], v[126:129], v[208:211], v[94:97]
	v_mfma_f32_16x16x32_bf16 v[90:93], v[138:141], v[208:211], v[90:93]
	v_mfma_f32_16x16x32_bf16 v[78:81], v[126:129], v[216:219], v[78:81]
	v_mfma_f32_16x16x32_bf16 v[74:77], v[138:141], v[216:219], v[74:77]
	v_mfma_f32_16x16x32_bf16 v[130:133], v[134:137], v[194:197], v[130:133]
	v_mfma_f32_16x16x32_bf16 v[122:125], v[142:145], v[194:197], v[122:125]
	v_mfma_f32_16x16x32_bf16 v[110:113], v[134:137], v[204:207], v[110:113]
	v_mfma_f32_16x16x32_bf16 v[106:109], v[142:145], v[204:207], v[106:109]
	v_mfma_f32_16x16x32_bf16 v[94:97], v[134:137], v[212:215], v[94:97]
	v_mfma_f32_16x16x32_bf16 v[90:93], v[142:145], v[212:215], v[90:93]
	v_mfma_f32_16x16x32_bf16 v[78:81], v[134:137], v[220:223], v[78:81]
	v_mfma_f32_16x16x32_bf16 v[74:77], v[142:145], v[220:223], v[74:77]
	v_mfma_f32_16x16x32_bf16 v[118:121], v[146:149], v[190:193], v[118:121]
	v_mfma_f32_16x16x32_bf16 v[114:117], v[154:157], v[190:193], v[114:117]
	v_mfma_f32_16x16x32_bf16 v[102:105], v[146:149], v[200:203], v[102:105]
	v_mfma_f32_16x16x32_bf16 v[98:101], v[154:157], v[200:203], v[98:101]
	v_mfma_f32_16x16x32_bf16 v[86:89], v[146:149], v[208:211], v[86:89]
	v_mfma_f32_16x16x32_bf16 v[82:85], v[154:157], v[208:211], v[82:85]
	v_mfma_f32_16x16x32_bf16 v[70:73], v[146:149], v[216:219], v[70:73]
	v_mfma_f32_16x16x32_bf16 v[66:69], v[154:157], v[216:219], v[66:69]
	v_mfma_f32_16x16x32_bf16 v[118:121], v[150:153], v[194:197], v[118:121]
	v_mfma_f32_16x16x32_bf16 v[114:117], v[186:189], v[194:197], v[114:117]
	v_mfma_f32_16x16x32_bf16 v[102:105], v[150:153], v[204:207], v[102:105]
	v_mfma_f32_16x16x32_bf16 v[98:101], v[186:189], v[204:207], v[98:101]
	v_mfma_f32_16x16x32_bf16 v[86:89], v[150:153], v[212:215], v[86:89]
	v_mfma_f32_16x16x32_bf16 v[82:85], v[186:189], v[212:215], v[82:85]
	v_mfma_f32_16x16x32_bf16 v[70:73], v[150:153], v[220:223], v[70:73]
	v_mfma_f32_16x16x32_bf16 v[66:69], v[186:189], v[220:223], v[66:69]
	s_setprio 0
	s_barrier
	s_add_i32 vcc_lo, vcc_lo, s29
	v_lshl_add_u64 v[224:225], s[96:97], 0, v[160:161]
	s_mov_b32 m0, vcc_lo
	ds_read_b128 v[190:193], v199 offset:16384
	ds_read_b128 v[194:197], v199 offset:17408
	ds_read_b128 v[200:203], v199 offset:18432
	ds_read_b128 v[204:207], v199 offset:19456
	ds_read_b128 v[208:211], v199 offset:20480
	ds_read_b128 v[212:215], v199 offset:21504
	ds_read_b128 v[216:219], v199 offset:22528
	ds_read_b128 v[220:223], v199 offset:23552
	global_load_lds_dwordx4 v[224:225], off
	s_add_i32 m0, vcc_lo, 0x2000
	v_lshl_add_u64 v[226:227], s[96:97], 0, v[164:165]
	s_add_u32 s96, s96, s62
	s_addc_u32 s97, s97, 0
	s_add_i32 s95, s95, s29
	global_load_lds_dwordx4 v[226:227], off
	v_lshl_add_u64 v[228:229], s[96:97], 0, v[160:161]
	s_mov_b32 m0, s95
	v_lshl_add_u64 v[230:231], s[96:97], 0, v[164:165]
	global_load_lds_dwordx4 v[228:229], off
	s_add_i32 m0, s95, 0x2000
	v_lshl_add_u64 v[232:233], s[20:21], 0, v[158:159]
	global_load_lds_dwordx4 v[230:231], off
	s_mov_b32 m0, s37
	v_lshl_add_u64 v[234:235], s[20:21], 0, v[162:163]
	global_load_lds_dwordx4 v[232:233], off
	s_mov_b32 m0, s40
	s_nop 0
	global_load_lds_dwordx4 v[234:235], off
	s_waitcnt vmcnt(8)
	s_waitcnt lgkmcnt(0)
	s_barrier
; #define PG8_STAGE(bufoff, gbase, voff) do { _Pragma("unroll") for (int _i = 0; _i < 2; ++_i) \
;         __builtin_amdgcn_global_load_lds((const unsigned*)((const char*)(gbase) + (voff)[_i]), (LAS unsigned*)(lds + (bufoff) + ldsw + _i * 8192), 16, 0, 0); } while (0)
; #define PG8_LDA(dst, b, h) do { _Pragma("unroll") for (int m = 0; m < 4; ++m) _Pragma("unroll") for (int k = 0; k < 2; ++k) dst[m][k] = *(const LAS bf16x8*)(lds + PG8_SA(b, h) + aoff + m * 2048 + k * 1024); } while (0)
; #define PG8_LDB(dst, b, h) do { _Pragma("unroll") for (int n = 0; n < 2; ++n) _Pragma("unroll") for (int k = 0; k < 2; ++k) dst[n][k] = *(const LAS bf16x8*)(lds + PG8_SB(b, h) + boff + n * 2048 + k * 1024); } while (0)
; #define PG8_MMA(ai, bj, At, Bt) do { __builtin_amdgcn_s_setprio(1); _Pragma("unroll") for (int m = 0; m < 4; ++m) _Pragma("unroll") for (int n = 0; n < 2; ++n) _Pragma("unroll") for (int k = 0; k < 2; ++k) \
;         acc[ai][bj][m][n] = __builtin_amdgcn_mfma_f32_16x16x32_bf16(Bt[n][k], At[m][k], acc[ai][bj][m][n], 0, 0, 0); __builtin_amdgcn_s_setprio(0); } while (0)
; #define PG8_WAIT_V(n) asm volatile("s_waitcnt vmcnt(" #n ")" ::: "memory")
; #define PG8_WAIT_L(n) asm volatile("s_waitcnt lgkmcnt(" #n ")" ::: "memory")
; #define PG8_BAR __builtin_amdgcn_s_barrier()
; #define PG8_SCHED __builtin_amdgcn_sched_barrier(0)
; template <class Epi, class Sched>
; __device__ __forceinline__ void gemm_phase(LAS unsigned char* lds, const Gemm g, const Sched S, const Epi E, const int tid) {
;     ...
;             PG8_WAIT_V(8); PG8_WAIT_L(0); PG8_BAR; PG8_MMA(1, 0, At, B0); PG8_MMA(1, 1, At, B1); PG8_BAR; PG8_SCHED;
;             PG8_LDB(B0, 1, 0); PG8_LDB(B1, 1, 1); PG8_SCHED; PG8_LDA(At, 1, 0); PG8_STAGE(PG8_SA(0, 1), a2 + hstepA, voffA);
;             PG8_WAIT_V(8); PG8_WAIT_L(0); PG8_BAR; PG8_MMA(0, 0, At, B0); PG8_MMA(0, 1, At, B1); PG8_BAR; PG8_SCHED;
	s_setprio 1
	s_waitcnt lgkmcnt(0)
	v_mfma_f32_16x16x32_bf16 v[62:65], v[126:129], v[190:193], v[62:65]
	v_mfma_f32_16x16x32_bf16 v[58:61], v[138:141], v[190:193], v[58:61]
	v_mfma_f32_16x16x32_bf16 v[46:49], v[126:129], v[200:203], v[46:49]
	v_mfma_f32_16x16x32_bf16 v[42:45], v[138:141], v[200:203], v[42:45]
	v_mfma_f32_16x16x32_bf16 v[30:33], v[126:129], v[208:211], v[30:33]
	v_mfma_f32_16x16x32_bf16 v[26:29], v[138:141], v[208:211], v[26:29]
	v_mfma_f32_16x16x32_bf16 v[14:17], v[126:129], v[216:219], v[14:17]
	v_mfma_f32_16x16x32_bf16 v[10:13], v[138:141], v[216:219], v[10:13]
	v_mfma_f32_16x16x32_bf16 v[62:65], v[134:137], v[194:197], v[62:65]
	v_mfma_f32_16x16x32_bf16 v[58:61], v[142:145], v[194:197], v[58:61]
	v_mfma_f32_16x16x32_bf16 v[46:49], v[134:137], v[204:207], v[46:49]
	v_mfma_f32_16x16x32_bf16 v[42:45], v[142:145], v[204:207], v[42:45]
	v_mfma_f32_16x16x32_bf16 v[30:33], v[134:137], v[212:215], v[30:33]
	v_mfma_f32_16x16x32_bf16 v[26:29], v[142:145], v[212:215], v[26:29]
	v_mfma_f32_16x16x32_bf16 v[14:17], v[134:137], v[220:223], v[14:17]
	v_mfma_f32_16x16x32_bf16 v[10:13], v[142:145], v[220:223], v[10:13]
	v_mfma_f32_16x16x32_bf16 v[54:57], v[146:149], v[190:193], v[54:57]
	v_mfma_f32_16x16x32_bf16 v[50:53], v[154:157], v[190:193], v[50:53]
	v_mfma_f32_16x16x32_bf16 v[38:41], v[146:149], v[200:203], v[38:41]
	v_mfma_f32_16x16x32_bf16 v[34:37], v[154:157], v[200:203], v[34:37]
	v_mfma_f32_16x16x32_bf16 v[22:25], v[146:149], v[208:211], v[22:25]
	v_mfma_f32_16x16x32_bf16 v[18:21], v[154:157], v[208:211], v[18:21]
	v_mfma_f32_16x16x32_bf16 v[6:9], v[146:149], v[216:219], v[6:9]
	v_mfma_f32_16x16x32_bf16 v[2:5], v[154:157], v[216:219], v[2:5]
	v_mfma_f32_16x16x32_bf16 v[54:57], v[150:153], v[194:197], v[54:57]
	v_mfma_f32_16x16x32_bf16 v[50:53], v[186:189], v[194:197], v[50:53]
	v_mfma_f32_16x16x32_bf16 v[38:41], v[150:153], v[204:207], v[38:41]
	v_mfma_f32_16x16x32_bf16 v[34:37], v[186:189], v[204:207], v[34:37]
	v_mfma_f32_16x16x32_bf16 v[22:25], v[150:153], v[212:215], v[22:25]
	v_mfma_f32_16x16x32_bf16 v[18:21], v[186:189], v[212:215], v[18:21]
	v_mfma_f32_16x16x32_bf16 v[6:9], v[150:153], v[220:223], v[6:9]
	v_mfma_f32_16x16x32_bf16 v[2:5], v[186:189], v[220:223], v[2:5]
	s_setprio 0
	s_barrier
	s_add_i32 s95, 0, 0x18000
	s_add_i32 s96, 0, 0x1c000
	v_add_u32_e32 v142, s95, v198
	v_add_u32_e32 v167, s96, v198
	ds_read_b128 v[126:129], v142
	ds_read_b128 v[134:137], v142 offset:1024
	ds_read_b128 v[138:141], v142 offset:2048
	ds_read_b128 v[142:145], v142 offset:3072
	ds_read_b128 v[146:149], v167
	ds_read_b128 v[150:153], v167 offset:1024
	ds_read_b128 v[154:157], v167 offset:2048
	ds_read_b128 v[186:189], v167 offset:3072
	s_add_u32 s20, s20, s62
	s_addc_u32 s21, s21, 0
	s_mov_b32 m0, s41
	v_lshl_add_u64 v[246:247], s[20:21], 0, v[158:159]
	ds_read_b128 v[190:193], v199 offset:32768
	ds_read_b128 v[194:197], v199 offset:33792
	ds_read_b128 v[200:203], v199 offset:34816
	ds_read_b128 v[204:207], v199 offset:35840
	ds_read_b128 v[208:211], v199 offset:36864
	ds_read_b128 v[212:215], v199 offset:37888
	ds_read_b128 v[216:219], v199 offset:38912
	ds_read_b128 v[220:223], v199 offset:39936
	global_load_lds_dwordx4 v[246:247], off
	v_lshl_add_u64 v[246:247], s[20:21], 0, v[162:163]
	s_mov_b32 m0, s42
	s_nop 0
	global_load_lds_dwordx4 v[246:247], off
	s_waitcnt vmcnt(8)
	s_waitcnt lgkmcnt(0)
	s_barrier
	s_setprio 1
	s_waitcnt lgkmcnt(0)
	v_mfma_f32_16x16x32_bf16 v[130:133], v[126:129], v[190:193], v[130:133]
	v_mfma_f32_16x16x32_bf16 v[122:125], v[138:141], v[190:193], v[122:125]
	v_mfma_f32_16x16x32_bf16 v[110:113], v[126:129], v[200:203], v[110:113]
	v_mfma_f32_16x16x32_bf16 v[106:109], v[138:141], v[200:203], v[106:109]
	v_mfma_f32_16x16x32_bf16 v[94:97], v[126:129], v[208:211], v[94:97]
	v_mfma_f32_16x16x32_bf16 v[90:93], v[138:141], v[208:211], v[90:93]
	v_mfma_f32_16x16x32_bf16 v[78:81], v[126:129], v[216:219], v[78:81]
	v_mfma_f32_16x16x32_bf16 v[74:77], v[138:141], v[216:219], v[74:77]
	v_mfma_f32_16x16x32_bf16 v[130:133], v[134:137], v[194:197], v[130:133]
	v_mfma_f32_16x16x32_bf16 v[122:125], v[142:145], v[194:197], v[122:125]
	v_mfma_f32_16x16x32_bf16 v[110:113], v[134:137], v[204:207], v[110:113]
	v_mfma_f32_16x16x32_bf16 v[106:109], v[142:145], v[204:207], v[106:109]
	v_mfma_f32_16x16x32_bf16 v[94:97], v[134:137], v[212:215], v[94:97]
	v_mfma_f32_16x16x32_bf16 v[90:93], v[142:145], v[212:215], v[90:93]
	v_mfma_f32_16x16x32_bf16 v[78:81], v[134:137], v[220:223], v[78:81]
	v_mfma_f32_16x16x32_bf16 v[74:77], v[142:145], v[220:223], v[74:77]
	v_mfma_f32_16x16x32_bf16 v[118:121], v[146:149], v[190:193], v[118:121]
	v_mfma_f32_16x16x32_bf16 v[114:117], v[154:157], v[190:193], v[114:117]
	v_mfma_f32_16x16x32_bf16 v[102:105], v[146:149], v[200:203], v[102:105]
	v_mfma_f32_16x16x32_bf16 v[98:101], v[154:157], v[200:203], v[98:101]
	v_mfma_f32_16x16x32_bf16 v[86:89], v[146:149], v[208:211], v[86:89]
	v_mfma_f32_16x16x32_bf16 v[82:85], v[154:157], v[208:211], v[82:85]
	v_mfma_f32_16x16x32_bf16 v[70:73], v[146:149], v[216:219], v[70:73]
	v_mfma_f32_16x16x32_bf16 v[66:69], v[154:157], v[216:219], v[66:69]
	v_mfma_f32_16x16x32_bf16 v[118:121], v[150:153], v[194:197], v[118:121]
	v_mfma_f32_16x16x32_bf16 v[114:117], v[186:189], v[194:197], v[114:117]
	v_mfma_f32_16x16x32_bf16 v[102:105], v[150:153], v[204:207], v[102:105]
	v_mfma_f32_16x16x32_bf16 v[98:101], v[186:189], v[204:207], v[98:101]
	v_mfma_f32_16x16x32_bf16 v[86:89], v[150:153], v[212:215], v[86:89]
	v_mfma_f32_16x16x32_bf16 v[82:85], v[186:189], v[212:215], v[82:85]
	v_mfma_f32_16x16x32_bf16 v[70:73], v[150:153], v[220:223], v[70:73]
	v_mfma_f32_16x16x32_bf16 v[66:69], v[186:189], v[220:223], v[66:69]
	s_setprio 0
	s_barrier
; #define PG8_STAGE(bufoff, gbase, voff) do { _Pragma("unroll") for (int _i = 0; _i < 2; ++_i) \
;         __builtin_amdgcn_global_load_lds((const unsigned*)((const char*)(gbase) + (voff)[_i]), (LAS unsigned*)(lds + (bufoff) + ldsw + _i * 8192), 16, 0, 0); } while (0)
; #define PG8_LDA(dst, b, h) do { _Pragma("unroll") for (int m = 0; m < 4; ++m) _Pragma("unroll") for (int k = 0; k < 2; ++k) dst[m][k] = *(const LAS bf16x8*)(lds + PG8_SA(b, h) + aoff + m * 2048 + k * 1024); } while (0)
; #define PG8_MMA(ai, bj, At, Bt) do { __builtin_amdgcn_s_setprio(1); _Pragma("unroll") for (int m = 0; m < 4; ++m) _Pragma("unroll") for (int n = 0; n < 2; ++n) _Pragma("unroll") for (int k = 0; k < 2; ++k) \
;         acc[ai][bj][m][n] = __builtin_amdgcn_mfma_f32_16x16x32_bf16(Bt[n][k], At[m][k], acc[ai][bj][m][n], 0, 0, 0); __builtin_amdgcn_s_setprio(0); } while (0)
; #define PG8_WAIT_V(n) asm volatile("s_waitcnt vmcnt(" #n ")" ::: "memory")
; #define PG8_WAIT_L(n) asm volatile("s_waitcnt lgkmcnt(" #n ")" ::: "memory")
; #define PG8_BAR __builtin_amdgcn_s_barrier()
; #define PG8_SCHED __builtin_amdgcn_sched_barrier(0)
; template <class Epi, class Sched>
; __device__ __forceinline__ void gemm_phase(LAS unsigned char* lds, const Gemm g, const Sched S, const Epi E, const int tid) {
;     ...
;             PG8_LDA(At, 1, 1); PG8_STAGE(PG8_SB(1, 0), b3, voffB); PG8_STAGE(PG8_SB(1, 1), b3 + hstepB, voffB); PG8_STAGE(PG8_SA(1, 0), a3, voffA);
;             PG8_WAIT_V(8); PG8_WAIT_L(0); PG8_BAR; PG8_MMA(1, 0, At, B0); PG8_MMA(1, 1, At, B1); PG8_BAR; PG8_SCHED;
;         }
	s_add_i32 s20, s95, s29
	v_lshl_add_u64 v[224:225], v[224:225], 0, s[64:65]
	s_mov_b32 m0, s20
	ds_read_b128 v[190:193], v199 offset:49152
	ds_read_b128 v[194:197], v199 offset:50176
	ds_read_b128 v[200:203], v199 offset:51200
	ds_read_b128 v[204:207], v199 offset:52224
	ds_read_b128 v[208:211], v199 offset:53248
	ds_read_b128 v[212:215], v199 offset:54272
	ds_read_b128 v[216:219], v199 offset:55296
	ds_read_b128 v[220:223], v199 offset:56320
	global_load_lds_dwordx4 v[224:225], off
	v_lshl_add_u64 v[224:225], v[226:227], 0, s[64:65]
	s_add_i32 m0, s20, 0x2000
	s_add_i32 s20, s96, s29
	global_load_lds_dwordx4 v[224:225], off
	v_lshl_add_u64 v[224:225], v[228:229], 0, s[64:65]
	s_mov_b32 m0, s20
	s_nop 0
	global_load_lds_dwordx4 v[224:225], off
	v_lshl_add_u64 v[224:225], v[230:231], 0, s[64:65]
	s_add_i32 m0, s20, 0x2000
	s_nop 0
	global_load_lds_dwordx4 v[224:225], off
	v_lshl_add_u64 v[224:225], v[232:233], 0, s[64:65]
	s_mov_b32 m0, s45
	s_nop 0
	global_load_lds_dwordx4 v[224:225], off
	v_lshl_add_u64 v[224:225], v[234:235], 0, s[64:65]
	s_mov_b32 m0, s46
	s_nop 0
	global_load_lds_dwordx4 v[224:225], off
	s_waitcnt vmcnt(8)
	s_waitcnt lgkmcnt(0)
	s_barrier
	s_setprio 1
	s_waitcnt lgkmcnt(0)
	v_mfma_f32_16x16x32_bf16 v[62:65], v[126:129], v[190:193], v[62:65]
	v_mfma_f32_16x16x32_bf16 v[58:61], v[138:141], v[190:193], v[58:61]
	v_mfma_f32_16x16x32_bf16 v[46:49], v[126:129], v[200:203], v[46:49]
	v_mfma_f32_16x16x32_bf16 v[42:45], v[138:141], v[200:203], v[42:45]
	v_mfma_f32_16x16x32_bf16 v[30:33], v[126:129], v[208:211], v[30:33]
	v_mfma_f32_16x16x32_bf16 v[26:29], v[138:141], v[208:211], v[26:29]
	v_mfma_f32_16x16x32_bf16 v[14:17], v[126:129], v[216:219], v[14:17]
	v_mfma_f32_16x16x32_bf16 v[10:13], v[138:141], v[216:219], v[10:13]
	v_mfma_f32_16x16x32_bf16 v[62:65], v[134:137], v[194:197], v[62:65]
	v_mfma_f32_16x16x32_bf16 v[58:61], v[142:145], v[194:197], v[58:61]
	v_mfma_f32_16x16x32_bf16 v[46:49], v[134:137], v[204:207], v[46:49]
	v_mfma_f32_16x16x32_bf16 v[42:45], v[142:145], v[204:207], v[42:45]
	v_mfma_f32_16x16x32_bf16 v[30:33], v[134:137], v[212:215], v[30:33]
	v_mfma_f32_16x16x32_bf16 v[26:29], v[142:145], v[212:215], v[26:29]
	v_mfma_f32_16x16x32_bf16 v[14:17], v[134:137], v[220:223], v[14:17]
	v_mfma_f32_16x16x32_bf16 v[10:13], v[142:145], v[220:223], v[10:13]
	v_mfma_f32_16x16x32_bf16 v[54:57], v[146:149], v[190:193], v[54:57]
	v_mfma_f32_16x16x32_bf16 v[50:53], v[154:157], v[190:193], v[50:53]
	v_mfma_f32_16x16x32_bf16 v[38:41], v[146:149], v[200:203], v[38:41]
	v_mfma_f32_16x16x32_bf16 v[34:37], v[154:157], v[200:203], v[34:37]
	v_mfma_f32_16x16x32_bf16 v[22:25], v[146:149], v[208:211], v[22:25]
	v_mfma_f32_16x16x32_bf16 v[18:21], v[154:157], v[208:211], v[18:21]
	v_mfma_f32_16x16x32_bf16 v[6:9], v[146:149], v[216:219], v[6:9]
	v_mfma_f32_16x16x32_bf16 v[2:5], v[154:157], v[216:219], v[2:5]
	v_mfma_f32_16x16x32_bf16 v[54:57], v[150:153], v[194:197], v[54:57]
	v_mfma_f32_16x16x32_bf16 v[50:53], v[186:189], v[194:197], v[50:53]
	v_mfma_f32_16x16x32_bf16 v[38:41], v[150:153], v[204:207], v[38:41]
	v_mfma_f32_16x16x32_bf16 v[34:37], v[186:189], v[204:207], v[34:37]
	v_mfma_f32_16x16x32_bf16 v[22:25], v[150:153], v[212:215], v[22:25]
	v_mfma_f32_16x16x32_bf16 v[18:21], v[186:189], v[212:215], v[18:21]
	v_mfma_f32_16x16x32_bf16 v[6:9], v[150:153], v[220:223], v[6:9]
	v_mfma_f32_16x16x32_bf16 v[2:5], v[186:189], v[220:223], v[2:5]
	s_setprio 0
	s_barrier
	s_add_u32 s92, s92, 0x100
	s_addc_u32 s93, s93, 0
	s_add_u32 s18, s18, 0x100
	s_addc_u32 s19, s19, 0
	s_cmp_ge_u32 s94, s47
	s_mov_b32 s20, s94
	s_cbranch_scc0 .LBB0_778
	s_and_b64 vcc, exec, s[12:13]
	s_cbranch_vccz .LBB0_781
	s_barrier

; #define PG8_STAGE(bufoff, gbase, voff) do { _Pragma("unroll") for (int _i = 0; _i < 2; ++_i) \
;         __builtin_amdgcn_global_load_lds((const unsigned*)((const char*)(gbase) + (voff)[_i]), (LAS unsigned*)(lds + (bufoff) + ldsw + _i * 8192), 16, 0, 0); } while (0)
; #define PG8_LDA(dst, b, h) do { _Pragma("unroll") for (int m = 0; m < 4; ++m) _Pragma("unroll") for (int k = 0; k < 2; ++k) dst[m][k] = *(const LAS bf16x8*)(lds + PG8_SA(b, h) + aoff + m * 2048 + k * 1024); } while (0)
; #define PG8_LDB(dst, b, h) do { _Pragma("unroll") for (int n = 0; n < 2; ++n) _Pragma("unroll") for (int k = 0; k < 2; ++k) dst[n][k] = *(const LAS bf16x8*)(lds + PG8_SB(b, h) + boff + n * 2048 + k * 1024); } while (0)
; #define PG8_MMA(ai, bj, At, Bt) do { __builtin_amdgcn_s_setprio(1); _Pragma("unroll") for (int m = 0; m < 4; ++m) _Pragma("unroll") for (int n = 0; n < 2; ++n) _Pragma("unroll") for (int k = 0; k < 2; ++k) \
;         acc[ai][bj][m][n] = __builtin_amdgcn_mfma_f32_16x16x32_bf16(Bt[n][k], At[m][k], acc[ai][bj][m][n], 0, 0, 0); __builtin_amdgcn_s_setprio(0); } while (0)
; #define PG8_WAIT_V(n) asm volatile("s_waitcnt vmcnt(" #n ")" ::: "memory")
; #define PG8_WAIT_L(n) asm volatile("s_waitcnt lgkmcnt(" #n ")" ::: "memory")
; #define PG8_BAR __builtin_amdgcn_s_barrier()
; #define PG8_SCHED __builtin_amdgcn_sched_barrier(0)
; template <class Epi, class Sched>
; __device__ __forceinline__ void gemm_phase(LAS unsigned char* lds, const Gemm g, const Sched S, const Epi E, const int tid) {
;     ...
;             PG8_LDB(B0, 0, 0); PG8_LDB(B1, 0, 1); PG8_SCHED; PG8_LDA(At, 0, 0); PG8_STAGE(PG8_SA(1, 1), a1 + hstepA, voffA);
;             PG8_WAIT_V(8); PG8_WAIT_L(0); PG8_BAR; PG8_MMA(0, 0, At, B0); PG8_MMA(0, 1, At, B1); PG8_BAR; PG8_SCHED;
;             PG8_LDA(At, 0, 1); PG8_STAGE(PG8_SB(0, 0), b2, voffB); PG8_STAGE(PG8_SB(0, 1), b2 + hstepB, voffB); PG8_STAGE(PG8_SA(0, 0), a2, voffA);
;             PG8_WAIT_V(8); PG8_WAIT_L(0); PG8_BAR; PG8_MMA(1, 0, At, B0); PG8_MMA(1, 1, At, B1); PG8_BAR; PG8_SCHED;
.LBB0_819:
	s_add_u32 s24, s22, 0xfffc0080
	s_addc_u32 s25, s23, -1
	s_add_i32 s85, 0, 0x10000
	s_cmp_eq_u32 s84, 12
	s_cselect_b32 s27, s9, s25
	s_cselect_b32 s26, s17, s24
	s_cselect_b32 s25, s15, s83
	s_cselect_b32 s24, s69, s82
	s_add_i32 s90, 0, 0x14000
	v_add_u32_e32 v154, s85, v165
	v_add_u32_e32 v162, s90, v165
	ds_read_b128 v[98:101], v154
	ds_read_b128 v[134:137], v154 offset:1024
	ds_read_b128 v[150:153], v154 offset:2048
	ds_read_b128 v[154:157], v154 offset:3072
	ds_read_b128 v[158:161], v162
	ds_read_b128 v[180:183], v162 offset:1024
	ds_read_b128 v[184:187], v162 offset:2048
	ds_read_b128 v[188:191], v162 offset:3072
	v_lshl_add_u64 v[162:163], s[22:23], 0, v[148:149]
	s_add_i32 m0, s40, 0xc000
	ds_read_b128 v[192:195], v166
	ds_read_b128 v[196:199], v166 offset:1024
	ds_read_b128 v[200:203], v166 offset:2048
	ds_read_b128 v[204:207], v166 offset:3072
	ds_read_b128 v[208:211], v166 offset:4096
	ds_read_b128 v[212:215], v166 offset:5120
	ds_read_b128 v[216:219], v166 offset:6144
	ds_read_b128 v[220:223], v166 offset:7168
	global_load_lds_dwordx4 v[162:163], off
	v_lshl_add_u64 v[162:163], s[22:23], 0, v[146:147]
	s_add_i32 m0, s40, 0xe000
	s_nop 0
	global_load_lds_dwordx4 v[162:163], off
	s_waitcnt vmcnt(8)
	s_waitcnt lgkmcnt(0)
	s_barrier
	s_setprio 1
	s_waitcnt lgkmcnt(0)
	v_mfma_f32_16x16x32_bf16 v[130:133], v[98:101], v[192:195], v[130:133]
	v_mfma_f32_16x16x32_bf16 v[118:121], v[150:153], v[192:195], v[118:121]
	v_mfma_f32_16x16x32_bf16 v[114:117], v[98:101], v[200:203], v[114:117]
	v_mfma_f32_16x16x32_bf16 v[102:105], v[150:153], v[200:203], v[102:105]
	v_mfma_f32_16x16x32_bf16 v[94:97], v[98:101], v[208:211], v[94:97]
	v_mfma_f32_16x16x32_bf16 v[82:85], v[150:153], v[208:211], v[82:85]
	v_mfma_f32_16x16x32_bf16 v[78:81], v[98:101], v[216:219], v[78:81]
	v_mfma_f32_16x16x32_bf16 v[66:69], v[150:153], v[216:219], v[66:69]
	v_mfma_f32_16x16x32_bf16 v[130:133], v[134:137], v[196:199], v[130:133]
	v_mfma_f32_16x16x32_bf16 v[118:121], v[154:157], v[196:199], v[118:121]
	v_mfma_f32_16x16x32_bf16 v[114:117], v[134:137], v[204:207], v[114:117]
	v_mfma_f32_16x16x32_bf16 v[102:105], v[154:157], v[204:207], v[102:105]
	v_mfma_f32_16x16x32_bf16 v[94:97], v[134:137], v[212:215], v[94:97]
	v_mfma_f32_16x16x32_bf16 v[82:85], v[154:157], v[212:215], v[82:85]
	v_mfma_f32_16x16x32_bf16 v[78:81], v[134:137], v[220:223], v[78:81]
	v_mfma_f32_16x16x32_bf16 v[66:69], v[154:157], v[220:223], v[66:69]
	v_mfma_f32_16x16x32_bf16 v[126:129], v[158:161], v[192:195], v[126:129]
	v_mfma_f32_16x16x32_bf16 v[122:125], v[184:187], v[192:195], v[122:125]
	v_mfma_f32_16x16x32_bf16 v[110:113], v[158:161], v[200:203], v[110:113]
	v_mfma_f32_16x16x32_bf16 v[106:109], v[184:187], v[200:203], v[106:109]
	v_mfma_f32_16x16x32_bf16 v[90:93], v[158:161], v[208:211], v[90:93]
	v_mfma_f32_16x16x32_bf16 v[86:89], v[184:187], v[208:211], v[86:89]
	v_mfma_f32_16x16x32_bf16 v[74:77], v[158:161], v[216:219], v[74:77]
	v_mfma_f32_16x16x32_bf16 v[70:73], v[184:187], v[216:219], v[70:73]
	v_mfma_f32_16x16x32_bf16 v[126:129], v[180:183], v[196:199], v[126:129]
	v_mfma_f32_16x16x32_bf16 v[122:125], v[188:191], v[196:199], v[122:125]
	v_mfma_f32_16x16x32_bf16 v[110:113], v[180:183], v[204:207], v[110:113]
	v_mfma_f32_16x16x32_bf16 v[106:109], v[188:191], v[204:207], v[106:109]
	v_mfma_f32_16x16x32_bf16 v[90:93], v[180:183], v[212:215], v[90:93]
	v_mfma_f32_16x16x32_bf16 v[86:89], v[188:191], v[212:215], v[86:89]
	v_mfma_f32_16x16x32_bf16 v[74:77], v[180:183], v[220:223], v[74:77]
	v_mfma_f32_16x16x32_bf16 v[70:73], v[188:191], v[220:223], v[70:73]
	s_setprio 0
	s_barrier
	s_add_i32 s85, s85, s28
	v_lshl_add_u64 v[162:163], s[24:25], 0, v[142:143]
	s_mov_b32 m0, s85
	ds_read_b128 v[192:195], v166 offset:16384
	ds_read_b128 v[196:199], v166 offset:17408
	ds_read_b128 v[200:203], v166 offset:18432
	ds_read_b128 v[204:207], v166 offset:19456
	ds_read_b128 v[208:211], v166 offset:20480
	ds_read_b128 v[212:215], v166 offset:21504
	ds_read_b128 v[216:219], v166 offset:22528
	ds_read_b128 v[220:223], v166 offset:23552
	global_load_lds_dwordx4 v[162:163], off
	s_add_i32 m0, s85, 0x2000
	s_add_u32 s88, s24, 0x40000
	v_lshl_add_u64 v[224:225], s[24:25], 0, v[138:139]
	s_addc_u32 s89, s25, 0
	s_add_i32 s85, s90, s28
	global_load_lds_dwordx4 v[224:225], off
	v_lshl_add_u64 v[226:227], s[88:89], 0, v[142:143]
	s_mov_b32 m0, s85
	v_lshl_add_u64 v[228:229], s[26:27], 0, v[140:141]
	global_load_lds_dwordx4 v[226:227], off
	v_lshl_add_u64 v[226:227], s[88:89], 0, v[138:139]
	s_add_i32 m0, s85, 0x2000
	s_nop 0
	global_load_lds_dwordx4 v[226:227], off
	v_lshl_add_u64 v[226:227], s[26:27], 0, v[144:145]
	s_mov_b32 m0, s40
	s_nop 0
	global_load_lds_dwordx4 v[226:227], off
	s_mov_b32 m0, s41
	s_nop 0
	global_load_lds_dwordx4 v[228:229], off
	s_waitcnt vmcnt(8)
	s_waitcnt lgkmcnt(0)
	s_barrier
; #define PG8_STAGE(bufoff, gbase, voff) do { _Pragma("unroll") for (int _i = 0; _i < 2; ++_i) \
;         __builtin_amdgcn_global_load_lds((const unsigned*)((const char*)(gbase) + (voff)[_i]), (LAS unsigned*)(lds + (bufoff) + ldsw + _i * 8192), 16, 0, 0); } while (0)
; #define PG8_LDA(dst, b, h) do { _Pragma("unroll") for (int m = 0; m < 4; ++m) _Pragma("unroll") for (int k = 0; k < 2; ++k) dst[m][k] = *(const LAS bf16x8*)(lds + PG8_SA(b, h) + aoff + m * 2048 + k * 1024); } while (0)
; #define PG8_LDB(dst, b, h) do { _Pragma("unroll") for (int n = 0; n < 2; ++n) _Pragma("unroll") for (int k = 0; k < 2; ++k) dst[n][k] = *(const LAS bf16x8*)(lds + PG8_SB(b, h) + boff + n * 2048 + k * 1024); } while (0)
; #define PG8_MMA(ai, bj, At, Bt) do { __builtin_amdgcn_s_setprio(1); _Pragma("unroll") for (int m = 0; m < 4; ++m) _Pragma("unroll") for (int n = 0; n < 2; ++n) _Pragma("unroll") for (int k = 0; k < 2; ++k) \
;         acc[ai][bj][m][n] = __builtin_amdgcn_mfma_f32_16x16x32_bf16(Bt[n][k], At[m][k], acc[ai][bj][m][n], 0, 0, 0); __builtin_amdgcn_s_setprio(0); } while (0)
; #define PG8_WAIT_V(n) asm volatile("s_waitcnt vmcnt(" #n ")" ::: "memory")
; #define PG8_WAIT_L(n) asm volatile("s_waitcnt lgkmcnt(" #n ")" ::: "memory")
; #define PG8_BAR __builtin_amdgcn_s_barrier()
; #define PG8_SCHED __builtin_amdgcn_sched_barrier(0)
; template <class Epi, class Sched>
; __device__ __forceinline__ void gemm_phase(LAS unsigned char* lds, const Gemm g, const Sched S, const Epi E, const int tid) {
;     ...
;             PG8_WAIT_V(8); PG8_WAIT_L(0); PG8_BAR; PG8_MMA(1, 0, At, B0); PG8_MMA(1, 1, At, B1); PG8_BAR; PG8_SCHED;
;             PG8_LDB(B0, 1, 0); PG8_LDB(B1, 1, 1); PG8_SCHED; PG8_LDA(At, 1, 0); PG8_STAGE(PG8_SA(0, 1), a2 + hstepA, voffA);
;             PG8_WAIT_V(8); PG8_WAIT_L(0); PG8_BAR; PG8_MMA(0, 0, At, B0); PG8_MMA(0, 1, At, B1); PG8_BAR; PG8_SCHED;
	s_setprio 1
	s_waitcnt lgkmcnt(0)
	v_mfma_f32_16x16x32_bf16 v[62:65], v[98:101], v[192:195], v[62:65]
	v_mfma_f32_16x16x32_bf16 v[50:53], v[150:153], v[192:195], v[50:53]
	v_mfma_f32_16x16x32_bf16 v[46:49], v[98:101], v[200:203], v[46:49]
	v_mfma_f32_16x16x32_bf16 v[34:37], v[150:153], v[200:203], v[34:37]
	v_mfma_f32_16x16x32_bf16 v[30:33], v[98:101], v[208:211], v[30:33]
	v_mfma_f32_16x16x32_bf16 v[18:21], v[150:153], v[208:211], v[18:21]
	v_mfma_f32_16x16x32_bf16 v[14:17], v[98:101], v[216:219], v[14:17]
	v_mfma_f32_16x16x32_bf16 v[6:9], v[150:153], v[216:219], v[6:9]
	v_mfma_f32_16x16x32_bf16 v[62:65], v[134:137], v[196:199], v[62:65]
	v_mfma_f32_16x16x32_bf16 v[50:53], v[154:157], v[196:199], v[50:53]
	v_mfma_f32_16x16x32_bf16 v[46:49], v[134:137], v[204:207], v[46:49]
	v_mfma_f32_16x16x32_bf16 v[34:37], v[154:157], v[204:207], v[34:37]
	v_mfma_f32_16x16x32_bf16 v[30:33], v[134:137], v[212:215], v[30:33]
	v_mfma_f32_16x16x32_bf16 v[18:21], v[154:157], v[212:215], v[18:21]
	v_mfma_f32_16x16x32_bf16 v[14:17], v[134:137], v[220:223], v[14:17]
	v_mfma_f32_16x16x32_bf16 v[6:9], v[154:157], v[220:223], v[6:9]
	v_mfma_f32_16x16x32_bf16 v[58:61], v[158:161], v[192:195], v[58:61]
	v_mfma_f32_16x16x32_bf16 v[54:57], v[184:187], v[192:195], v[54:57]
	v_mfma_f32_16x16x32_bf16 v[42:45], v[158:161], v[200:203], v[42:45]
	v_mfma_f32_16x16x32_bf16 v[38:41], v[184:187], v[200:203], v[38:41]
	v_mfma_f32_16x16x32_bf16 v[26:29], v[158:161], v[208:211], v[26:29]
	v_mfma_f32_16x16x32_bf16 v[22:25], v[184:187], v[208:211], v[22:25]
	v_mfma_f32_16x16x32_bf16 v[10:13], v[158:161], v[216:219], v[10:13]
	v_mfma_f32_16x16x32_bf16 v[2:5], v[184:187], v[216:219], v[2:5]
	v_mfma_f32_16x16x32_bf16 v[58:61], v[180:183], v[196:199], v[58:61]
	v_mfma_f32_16x16x32_bf16 v[54:57], v[188:191], v[196:199], v[54:57]
	v_mfma_f32_16x16x32_bf16 v[42:45], v[180:183], v[204:207], v[42:45]
	v_mfma_f32_16x16x32_bf16 v[38:41], v[188:191], v[204:207], v[38:41]
	v_mfma_f32_16x16x32_bf16 v[26:29], v[180:183], v[212:215], v[26:29]
	v_mfma_f32_16x16x32_bf16 v[22:25], v[188:191], v[212:215], v[22:25]
	v_mfma_f32_16x16x32_bf16 v[10:13], v[180:183], v[220:223], v[10:13]
	v_mfma_f32_16x16x32_bf16 v[2:5], v[188:191], v[220:223], v[2:5]
	s_setprio 0
	s_barrier
	s_add_i32 s85, 0, 0x18000
	s_add_i32 s88, 0, 0x1c000
	v_add_u32_e32 v154, s85, v165
	v_add_u32_e32 v167, s88, v165
	ds_read_b128 v[98:101], v154
	ds_read_b128 v[134:137], v154 offset:1024
	ds_read_b128 v[150:153], v154 offset:2048
	ds_read_b128 v[154:157], v154 offset:3072
	ds_read_b128 v[158:161], v167
	ds_read_b128 v[180:183], v167 offset:1024
	ds_read_b128 v[184:187], v167 offset:2048
	ds_read_b128 v[188:191], v167 offset:3072
	s_add_u32 s26, s26, 0x40000
	s_addc_u32 s27, s27, 0
	s_mov_b32 m0, s42
	v_lshl_add_u64 v[230:231], s[26:27], 0, v[144:145]
	ds_read_b128 v[192:195], v166 offset:32768
	ds_read_b128 v[196:199], v166 offset:33792
	ds_read_b128 v[200:203], v166 offset:34816
	ds_read_b128 v[204:207], v166 offset:35840
	ds_read_b128 v[208:211], v166 offset:36864
	ds_read_b128 v[212:215], v166 offset:37888
	ds_read_b128 v[216:219], v166 offset:38912
	ds_read_b128 v[220:223], v166 offset:39936
	global_load_lds_dwordx4 v[230:231], off
	v_lshl_add_u64 v[230:231], s[26:27], 0, v[140:141]
	s_mov_b32 m0, s43
	s_nop 0
	global_load_lds_dwordx4 v[230:231], off
	s_waitcnt vmcnt(8)
	s_waitcnt lgkmcnt(0)
	s_barrier
	s_setprio 1
	s_waitcnt lgkmcnt(0)
	v_mfma_f32_16x16x32_bf16 v[130:133], v[98:101], v[192:195], v[130:133]
	v_mfma_f32_16x16x32_bf16 v[118:121], v[150:153], v[192:195], v[118:121]
	v_mfma_f32_16x16x32_bf16 v[114:117], v[98:101], v[200:203], v[114:117]
	v_mfma_f32_16x16x32_bf16 v[102:105], v[150:153], v[200:203], v[102:105]
	v_mfma_f32_16x16x32_bf16 v[94:97], v[98:101], v[208:211], v[94:97]
	v_mfma_f32_16x16x32_bf16 v[82:85], v[150:153], v[208:211], v[82:85]
	v_mfma_f32_16x16x32_bf16 v[78:81], v[98:101], v[216:219], v[78:81]
	v_mfma_f32_16x16x32_bf16 v[66:69], v[150:153], v[216:219], v[66:69]
	v_mfma_f32_16x16x32_bf16 v[130:133], v[134:137], v[196:199], v[130:133]
	v_mfma_f32_16x16x32_bf16 v[118:121], v[154:157], v[196:199], v[118:121]
	v_mfma_f32_16x16x32_bf16 v[114:117], v[134:137], v[204:207], v[114:117]
	v_mfma_f32_16x16x32_bf16 v[102:105], v[154:157], v[204:207], v[102:105]
	v_mfma_f32_16x16x32_bf16 v[94:97], v[134:137], v[212:215], v[94:97]
	v_mfma_f32_16x16x32_bf16 v[82:85], v[154:157], v[212:215], v[82:85]
	v_mfma_f32_16x16x32_bf16 v[78:81], v[134:137], v[220:223], v[78:81]
	v_mfma_f32_16x16x32_bf16 v[66:69], v[154:157], v[220:223], v[66:69]
	v_mfma_f32_16x16x32_bf16 v[126:129], v[158:161], v[192:195], v[126:129]
	v_mfma_f32_16x16x32_bf16 v[122:125], v[184:187], v[192:195], v[122:125]
	v_mfma_f32_16x16x32_bf16 v[110:113], v[158:161], v[200:203], v[110:113]
	v_mfma_f32_16x16x32_bf16 v[106:109], v[184:187], v[200:203], v[106:109]
	v_mfma_f32_16x16x32_bf16 v[90:93], v[158:161], v[208:211], v[90:93]
	v_mfma_f32_16x16x32_bf16 v[86:89], v[184:187], v[208:211], v[86:89]
	v_mfma_f32_16x16x32_bf16 v[74:77], v[158:161], v[216:219], v[74:77]
	v_mfma_f32_16x16x32_bf16 v[70:73], v[184:187], v[216:219], v[70:73]
	v_mfma_f32_16x16x32_bf16 v[126:129], v[180:183], v[196:199], v[126:129]
	v_mfma_f32_16x16x32_bf16 v[122:125], v[188:191], v[196:199], v[122:125]
	v_mfma_f32_16x16x32_bf16 v[110:113], v[180:183], v[204:207], v[110:113]
	v_mfma_f32_16x16x32_bf16 v[106:109], v[188:191], v[204:207], v[106:109]
	v_mfma_f32_16x16x32_bf16 v[90:93], v[180:183], v[212:215], v[90:93]
	v_mfma_f32_16x16x32_bf16 v[86:89], v[188:191], v[212:215], v[86:89]
	v_mfma_f32_16x16x32_bf16 v[74:77], v[180:183], v[220:223], v[74:77]
	v_mfma_f32_16x16x32_bf16 v[70:73], v[188:191], v[220:223], v[70:73]
	s_setprio 0
	s_barrier
; #define PG8_STAGE(bufoff, gbase, voff) do { _Pragma("unroll") for (int _i = 0; _i < 2; ++_i) \
;         __builtin_amdgcn_global_load_lds((const unsigned*)((const char*)(gbase) + (voff)[_i]), (LAS unsigned*)(lds + (bufoff) + ldsw + _i * 8192), 16, 0, 0); } while (0)
; #define PG8_LDA(dst, b, h) do { _Pragma("unroll") for (int m = 0; m < 4; ++m) _Pragma("unroll") for (int k = 0; k < 2; ++k) dst[m][k] = *(const LAS bf16x8*)(lds + PG8_SA(b, h) + aoff + m * 2048 + k * 1024); } while (0)
; #define PG8_MMA(ai, bj, At, Bt) do { __builtin_amdgcn_s_setprio(1); _Pragma("unroll") for (int m = 0; m < 4; ++m) _Pragma("unroll") for (int n = 0; n < 2; ++n) _Pragma("unroll") for (int k = 0; k < 2; ++k) \
;         acc[ai][bj][m][n] = __builtin_amdgcn_mfma_f32_16x16x32_bf16(Bt[n][k], At[m][k], acc[ai][bj][m][n], 0, 0, 0); __builtin_amdgcn_s_setprio(0); } while (0)
; #define PG8_WAIT_V(n) asm volatile("s_waitcnt vmcnt(" #n ")" ::: "memory")
; #define PG8_WAIT_L(n) asm volatile("s_waitcnt lgkmcnt(" #n ")" ::: "memory")
; #define PG8_BAR __builtin_amdgcn_s_barrier()
; #define PG8_SCHED __builtin_amdgcn_sched_barrier(0)
; template <class Epi, class Sched>
; __device__ __forceinline__ void gemm_phase(LAS unsigned char* lds, const Gemm g, const Sched S, const Epi E, const int tid) {
;     ...
;             PG8_LDA(At, 1, 1); PG8_STAGE(PG8_SB(1, 0), b3, voffB); PG8_STAGE(PG8_SB(1, 1), b3 + hstepB, voffB); PG8_STAGE(PG8_SA(1, 0), a3, voffA);
;             PG8_WAIT_V(8); PG8_WAIT_L(0); PG8_BAR; PG8_MMA(1, 0, At, B0); PG8_MMA(1, 1, At, B1); PG8_BAR; PG8_SCHED;
;         }
	s_add_i32 s26, s85, s28
	v_lshl_add_u64 v[162:163], v[162:163], 0, s[64:65]
	s_mov_b32 m0, s26
	ds_read_b128 v[192:195], v166 offset:49152
	ds_read_b128 v[196:199], v166 offset:50176
	ds_read_b128 v[200:203], v166 offset:51200
	ds_read_b128 v[204:207], v166 offset:52224
	ds_read_b128 v[208:211], v166 offset:53248
	ds_read_b128 v[212:215], v166 offset:54272
	ds_read_b128 v[216:219], v166 offset:55296
	ds_read_b128 v[220:223], v166 offset:56320
	global_load_lds_dwordx4 v[162:163], off
	s_add_i32 m0, s26, 0x2000
	s_add_u32 s24, s24, 0x40080
	v_lshl_add_u64 v[162:163], v[224:225], 0, s[64:65]
	s_addc_u32 s25, s25, 0
	s_add_i32 s26, s88, s28
	global_load_lds_dwordx4 v[162:163], off
	v_lshl_add_u64 v[162:163], s[24:25], 0, v[142:143]
	s_mov_b32 m0, s26
	s_nop 0
	global_load_lds_dwordx4 v[162:163], off
	v_lshl_add_u64 v[162:163], s[24:25], 0, v[138:139]
	s_add_i32 m0, s26, 0x2000
	s_nop 0
	global_load_lds_dwordx4 v[162:163], off
	v_lshl_add_u64 v[162:163], v[226:227], 0, s[64:65]
	s_mov_b32 m0, s46
	s_nop 0
	global_load_lds_dwordx4 v[162:163], off
	v_lshl_add_u64 v[162:163], v[228:229], 0, s[64:65]
	s_mov_b32 m0, s47
	s_nop 0
	global_load_lds_dwordx4 v[162:163], off
	s_waitcnt vmcnt(8)
	s_waitcnt lgkmcnt(0)
	s_barrier
	s_setprio 1
	s_waitcnt lgkmcnt(0)
	v_mfma_f32_16x16x32_bf16 v[62:65], v[98:101], v[192:195], v[62:65]
	v_mfma_f32_16x16x32_bf16 v[50:53], v[150:153], v[192:195], v[50:53]
	v_mfma_f32_16x16x32_bf16 v[46:49], v[98:101], v[200:203], v[46:49]
	v_mfma_f32_16x16x32_bf16 v[34:37], v[150:153], v[200:203], v[34:37]
	v_mfma_f32_16x16x32_bf16 v[30:33], v[98:101], v[208:211], v[30:33]
	v_mfma_f32_16x16x32_bf16 v[18:21], v[150:153], v[208:211], v[18:21]
	v_mfma_f32_16x16x32_bf16 v[14:17], v[98:101], v[216:219], v[14:17]
	v_mfma_f32_16x16x32_bf16 v[6:9], v[150:153], v[216:219], v[6:9]
	v_mfma_f32_16x16x32_bf16 v[62:65], v[134:137], v[196:199], v[62:65]
	v_mfma_f32_16x16x32_bf16 v[50:53], v[154:157], v[196:199], v[50:53]
	v_mfma_f32_16x16x32_bf16 v[46:49], v[134:137], v[204:207], v[46:49]
	v_mfma_f32_16x16x32_bf16 v[34:37], v[154:157], v[204:207], v[34:37]
	v_mfma_f32_16x16x32_bf16 v[30:33], v[134:137], v[212:215], v[30:33]
	v_mfma_f32_16x16x32_bf16 v[18:21], v[154:157], v[212:215], v[18:21]
	v_mfma_f32_16x16x32_bf16 v[14:17], v[134:137], v[220:223], v[14:17]
	v_mfma_f32_16x16x32_bf16 v[6:9], v[154:157], v[220:223], v[6:9]
	v_mfma_f32_16x16x32_bf16 v[58:61], v[158:161], v[192:195], v[58:61]
	v_mfma_f32_16x16x32_bf16 v[54:57], v[184:187], v[192:195], v[54:57]
	v_mfma_f32_16x16x32_bf16 v[42:45], v[158:161], v[200:203], v[42:45]
	v_mfma_f32_16x16x32_bf16 v[38:41], v[184:187], v[200:203], v[38:41]
	v_mfma_f32_16x16x32_bf16 v[26:29], v[158:161], v[208:211], v[26:29]
	v_mfma_f32_16x16x32_bf16 v[22:25], v[184:187], v[208:211], v[22:25]
	v_mfma_f32_16x16x32_bf16 v[10:13], v[158:161], v[216:219], v[10:13]
	v_mfma_f32_16x16x32_bf16 v[2:5], v[184:187], v[216:219], v[2:5]
	v_mfma_f32_16x16x32_bf16 v[58:61], v[180:183], v[196:199], v[58:61]
	v_mfma_f32_16x16x32_bf16 v[54:57], v[188:191], v[196:199], v[54:57]
	v_mfma_f32_16x16x32_bf16 v[42:45], v[180:183], v[204:207], v[42:45]
	v_mfma_f32_16x16x32_bf16 v[38:41], v[188:191], v[204:207], v[38:41]
	v_mfma_f32_16x16x32_bf16 v[26:29], v[180:183], v[212:215], v[26:29]
	v_mfma_f32_16x16x32_bf16 v[22:25], v[188:191], v[212:215], v[22:25]
	v_mfma_f32_16x16x32_bf16 v[10:13], v[180:183], v[220:223], v[10:13]
	v_mfma_f32_16x16x32_bf16 v[2:5], v[188:191], v[220:223], v[2:5]
	s_setprio 0
	s_barrier
	s_add_i32 s84, s84, 2
	s_add_u32 s82, s82, 0x100
	s_addc_u32 s83, s83, 0
	s_add_u32 s22, s22, 0x100
	s_addc_u32 s23, s23, 0
	s_cmp_gt_u32 s84, 13
	s_cbranch_scc0 .LBB0_819
	s_and_b64 vcc, exec, s[12:13]
	s_cbranch_vccz .LBB0_822
	s_barrier
